# stacked: full-line LDS-DMA re-layout + 4/4/4/4 per-phase DMA balancing in all four GEMM K-loops
# speedup vs baseline: 1.0121x; 1.0033x over previous
; #define PG8_STAGE(bufoff, gbase, voff) do { _Pragma("unroll") for (int _i = 0; _i < 2; ++_i) \
;         __builtin_amdgcn_global_load_lds((const unsigned*)((const char*)(gbase) + (voff)[_i]), (LAS unsigned*)(lds + (bufoff) + ldsw + _i * 8192), 16, 0, 0); } while (0)
; #define PG8_LDA(dst, b, h) do { _Pragma("unroll") for (int m = 0; m < 4; ++m) _Pragma("unroll") for (int k = 0; k < 2; ++k) dst[m][k] = *(const LAS bf16x8*)(lds + PG8_SA(b, h) + aoff + m * 2048 + k * 1024); } while (0)
; #define PG8_LDB(dst, b, h) do { _Pragma("unroll") for (int n = 0; n < 2; ++n) _Pragma("unroll") for (int k = 0; k < 2; ++k) dst[n][k] = *(const LAS bf16x8*)(lds + PG8_SB(b, h) + boff + n * 2048 + k * 1024); } while (0)
; #define PG8_MMA(ai, bj, At, Bt) do { __builtin_amdgcn_s_setprio(3); _Pragma("unroll") for (int m = 0; m < 4; ++m) _Pragma("unroll") for (int n = 0; n < 2; ++n) _Pragma("unroll") for (int k = 0; k < 2; ++k) \
;         acc[ai][bj][m][n] = __builtin_amdgcn_mfma_f32_16x16x32_bf16(Bt[n][k], At[m][k], acc[ai][bj][m][n], 0, 0, 0); __builtin_amdgcn_s_setprio(0); } while (0)
; #define PG8_WAIT_V(n) asm volatile("s_waitcnt vmcnt(" #n ")" ::: "memory")
; #define PG8_WAIT_L(n) asm volatile("s_waitcnt lgkmcnt(" #n ")" ::: "memory")
; #define PG8_BAR __builtin_amdgcn_s_barrier()
; #define PG8_SCHED __builtin_amdgcn_sched_barrier(0)
; template <class Epi, class Sched, bool ALIGN_EPI = false, bool SP2 = false>
; __device__ __forceinline__ void gemm_phase(LAS unsigned char* lds, const Gemm g, const Sched& S, const Epi& E) {
;     ...
;             PG8_LDB(B0, 0, 0); PG8_LDB(B1, 0, 1); PG8_SCHED; PG8_LDA(At, 0, 0); PG8_STAGE(PG8_SA(1, 1), a1 + hsA, voffA);
;             PG8_WAIT_V(8); PG8_WAIT_L(0); PG8_BAR; PG8_MMA(0, 0, At, B0); PG8_MMA(0, 1, At, B1); PG8_BAR; PG8_SCHED;
;             PG8_LDA(At, 0, 1); PG8_STAGE(PG8_SB(0, 0), b2, voffB); PG8_STAGE(PG8_SB(0, 1), b2 + hsB, voffB); PG8_STAGE(PG8_SA(0, 0), a2, voffA);
;             PG8_WAIT_V(8); PG8_WAIT_L(0); PG8_BAR; PG8_MMA(1, 0, At, B0); PG8_MMA(1, 1, At, B1); PG8_BAR; PG8_SCHED;
.LBB0_64:
	ds_read_b128 v[128:131], v158
	ds_read_b128 v[150:153], v251
	ds_read_b128 v[166:169], v158 offset:2048
	ds_read_b128 v[170:173], v251 offset:2048
	ds_read_b128 v[174:177], v159
	ds_read_b128 v[178:181], v252
	ds_read_b128 v[182:185], v159 offset:2048
	ds_read_b128 v[186:189], v252 offset:2048
	s_add_u32 s6, s4, 0xffefc080
	s_addc_u32 s7, s5, -1
	s_cmp_eq_u32 s91, 60
	s_cselect_b32 s63, s59, s7
	s_cselect_b32 s62, s58, s6
	s_cselect_b32 s7, s61, s90
	s_cselect_b32 s6, s60, s89
	s_sub_u32 s100, s4, 0x104000
	s_subb_u32 s101, s5, 0
	v_lshl_add_u64 v[242:243], s[100:101], 0, v[132:133]
	s_mov_b32 m0, s76
	v_lshl_add_u64 v[244:245], s[100:101], 0, v[136:137]
	global_load_lds_dwordx4 v[242:243], off
	s_mov_b32 m0, s77
	s_nop 0
	global_load_lds_dwordx4 v[244:245], off
	v_lshl_add_u64 v[226:227], s[4:5], 0, v[142:143]
	s_add_i32 m0, s68, 0xc000
	ds_read_b128 v[190:193], v160
	ds_read_b128 v[194:197], v250
	ds_read_b128 v[198:201], v160 offset:2048
	ds_read_b128 v[206:209], v250 offset:2048
	ds_read_b128 v[210:213], v160 offset:4096
	ds_read_b128 v[214:217], v250 offset:4096
	ds_read_b128 v[218:221], v160 offset:6144
	ds_read_b128 v[222:225], v250 offset:6144
	global_load_lds_dwordx4 v[226:227], off
	v_lshl_add_u64 v[226:227], s[4:5], 0, v[144:145]
	s_add_i32 m0, s68, 0xe000
	s_nop 0
	global_load_lds_dwordx4 v[226:227], off
	s_waitcnt vmcnt(8)
	s_waitcnt lgkmcnt(0)
	s_barrier
	s_setprio 3
	s_waitcnt lgkmcnt(0)
	v_mfma_f32_16x16x32_bf16 v[124:127], v[128:131], v[190:193], v[124:127]
	v_mfma_f32_16x16x32_bf16 v[120:123], v[166:169], v[190:193], v[120:123]
	v_mfma_f32_16x16x32_bf16 v[108:111], v[128:131], v[198:201], v[108:111]
	v_mfma_f32_16x16x32_bf16 v[104:107], v[166:169], v[198:201], v[104:107]
	v_mfma_f32_16x16x32_bf16 v[92:95], v[128:131], v[210:213], v[92:95]
	v_mfma_f32_16x16x32_bf16 v[88:91], v[166:169], v[210:213], v[88:91]
	v_mfma_f32_16x16x32_bf16 v[76:79], v[128:131], v[218:221], v[76:79]
	v_mfma_f32_16x16x32_bf16 v[72:75], v[166:169], v[218:221], v[72:75]
	v_mfma_f32_16x16x32_bf16 v[124:127], v[150:153], v[194:197], v[124:127]
	v_mfma_f32_16x16x32_bf16 v[120:123], v[170:173], v[194:197], v[120:123]
	v_mfma_f32_16x16x32_bf16 v[108:111], v[150:153], v[206:209], v[108:111]
	v_mfma_f32_16x16x32_bf16 v[104:107], v[170:173], v[206:209], v[104:107]
	v_mfma_f32_16x16x32_bf16 v[92:95], v[150:153], v[214:217], v[92:95]
	v_mfma_f32_16x16x32_bf16 v[88:91], v[170:173], v[214:217], v[88:91]
	v_mfma_f32_16x16x32_bf16 v[76:79], v[150:153], v[222:225], v[76:79]
	v_mfma_f32_16x16x32_bf16 v[72:75], v[170:173], v[222:225], v[72:75]
	s_setprio 0
	s_setprio 3
	v_mfma_f32_16x16x32_bf16 v[116:119], v[174:177], v[190:193], v[116:119]
	v_mfma_f32_16x16x32_bf16 v[112:115], v[182:185], v[190:193], v[112:115]
	v_mfma_f32_16x16x32_bf16 v[100:103], v[174:177], v[198:201], v[100:103]
	v_mfma_f32_16x16x32_bf16 v[96:99], v[182:185], v[198:201], v[96:99]
	v_mfma_f32_16x16x32_bf16 v[84:87], v[174:177], v[210:213], v[84:87]
	v_mfma_f32_16x16x32_bf16 v[80:83], v[182:185], v[210:213], v[80:83]
	v_mfma_f32_16x16x32_bf16 v[68:71], v[174:177], v[218:221], v[68:71]
	v_mfma_f32_16x16x32_bf16 v[64:67], v[182:185], v[218:221], v[64:67]
	v_mfma_f32_16x16x32_bf16 v[116:119], v[178:181], v[194:197], v[116:119]
	v_mfma_f32_16x16x32_bf16 v[112:115], v[186:189], v[194:197], v[112:115]
	v_mfma_f32_16x16x32_bf16 v[100:103], v[178:181], v[206:209], v[100:103]
	v_mfma_f32_16x16x32_bf16 v[96:99], v[186:189], v[206:209], v[96:99]
	v_mfma_f32_16x16x32_bf16 v[84:87], v[178:181], v[214:217], v[84:87]
	v_mfma_f32_16x16x32_bf16 v[80:83], v[186:189], v[214:217], v[80:83]
	v_mfma_f32_16x16x32_bf16 v[68:71], v[178:181], v[222:225], v[68:71]
	v_mfma_f32_16x16x32_bf16 v[64:67], v[186:189], v[222:225], v[64:67]
	s_setprio 0
	s_barrier
	s_add_i32 s92, s82, s67
	v_lshl_add_u64 v[226:227], s[6:7], 0, v[134:135]
	s_mov_b32 m0, s92
	ds_read_b128 v[190:193], v160 offset:16384
	ds_read_b128 v[194:197], v250 offset:16384
	ds_read_b128 v[198:201], v160 offset:18432
	ds_read_b128 v[206:209], v250 offset:18432
	ds_read_b128 v[210:213], v160 offset:20480
	ds_read_b128 v[214:217], v250 offset:20480
	ds_read_b128 v[218:221], v160 offset:22528
	ds_read_b128 v[222:225], v250 offset:22528
	global_load_lds_dwordx4 v[226:227], off
	s_add_i32 m0, s92, 0x2000
	s_add_u32 s92, s6, 0x41000
	v_lshl_add_u64 v[228:229], s[6:7], 0, v[138:139]
	s_addc_u32 s93, s7, 0
	s_add_i32 s94, s83, s67
	global_load_lds_dwordx4 v[228:229], off
	v_lshl_add_u64 v[230:231], s[92:93], 0, v[134:135]
	s_mov_b32 m0, s94
	s_nop 0
	global_load_lds_dwordx4 v[230:231], off
	v_lshl_add_u64 v[230:231], s[92:93], 0, v[138:139]
	s_add_i32 m0, s94, 0x2000
	s_nop 0
	global_load_lds_dwordx4 v[230:231], off
	s_waitcnt vmcnt(6)
	s_waitcnt lgkmcnt(0)
	s_barrier
; #define PG8_STAGE(bufoff, gbase, voff) do { _Pragma("unroll") for (int _i = 0; _i < 2; ++_i) \
;         __builtin_amdgcn_global_load_lds((const unsigned*)((const char*)(gbase) + (voff)[_i]), (LAS unsigned*)(lds + (bufoff) + ldsw + _i * 8192), 16, 0, 0); } while (0)
; #define PG8_LDA(dst, b, h) do { _Pragma("unroll") for (int m = 0; m < 4; ++m) _Pragma("unroll") for (int k = 0; k < 2; ++k) dst[m][k] = *(const LAS bf16x8*)(lds + PG8_SA(b, h) + aoff + m * 2048 + k * 1024); } while (0)
; #define PG8_LDB(dst, b, h) do { _Pragma("unroll") for (int n = 0; n < 2; ++n) _Pragma("unroll") for (int k = 0; k < 2; ++k) dst[n][k] = *(const LAS bf16x8*)(lds + PG8_SB(b, h) + boff + n * 2048 + k * 1024); } while (0)
; #define PG8_MMA(ai, bj, At, Bt) do { __builtin_amdgcn_s_setprio(3); _Pragma("unroll") for (int m = 0; m < 4; ++m) _Pragma("unroll") for (int n = 0; n < 2; ++n) _Pragma("unroll") for (int k = 0; k < 2; ++k) \
;         acc[ai][bj][m][n] = __builtin_amdgcn_mfma_f32_16x16x32_bf16(Bt[n][k], At[m][k], acc[ai][bj][m][n], 0, 0, 0); __builtin_amdgcn_s_setprio(0); } while (0)
; #define PG8_WAIT_V(n) asm volatile("s_waitcnt vmcnt(" #n ")" ::: "memory")
; #define PG8_WAIT_L(n) asm volatile("s_waitcnt lgkmcnt(" #n ")" ::: "memory")
; #define PG8_BAR __builtin_amdgcn_s_barrier()
; #define PG8_SCHED __builtin_amdgcn_sched_barrier(0)
; template <class Epi, class Sched, bool ALIGN_EPI = false, bool SP2 = false>
; __device__ __forceinline__ void gemm_phase(LAS unsigned char* lds, const Gemm g, const Sched& S, const Epi& E) {
;     ...
;             PG8_WAIT_V(8); PG8_WAIT_L(0); PG8_BAR; PG8_MMA(1, 0, At, B0); PG8_MMA(1, 1, At, B1); PG8_BAR; PG8_SCHED;
;             PG8_LDB(B0, 1, 0); PG8_LDB(B1, 1, 1); PG8_SCHED; PG8_LDA(At, 1, 0); PG8_STAGE(PG8_SA(0, 1), a2 + hsA, voffA);
;             PG8_WAIT_V(8); PG8_WAIT_L(0); PG8_BAR; PG8_MMA(0, 0, At, B0); PG8_MMA(0, 1, At, B1); PG8_BAR; PG8_SCHED;
	s_setprio 3
	s_waitcnt lgkmcnt(0)
	v_mfma_f32_16x16x32_bf16 v[60:63], v[128:131], v[190:193], v[60:63]
	v_mfma_f32_16x16x32_bf16 v[56:59], v[166:169], v[190:193], v[56:59]
	v_mfma_f32_16x16x32_bf16 v[44:47], v[128:131], v[198:201], v[44:47]
	v_mfma_f32_16x16x32_bf16 v[40:43], v[166:169], v[198:201], v[40:43]
	v_mfma_f32_16x16x32_bf16 v[28:31], v[128:131], v[210:213], v[28:31]
	v_mfma_f32_16x16x32_bf16 v[24:27], v[166:169], v[210:213], v[24:27]
	v_mfma_f32_16x16x32_bf16 v[12:15], v[128:131], v[218:221], v[12:15]
	v_mfma_f32_16x16x32_bf16 v[8:11], v[166:169], v[218:221], v[8:11]
	v_mfma_f32_16x16x32_bf16 v[60:63], v[150:153], v[194:197], v[60:63]
	v_mfma_f32_16x16x32_bf16 v[56:59], v[170:173], v[194:197], v[56:59]
	v_mfma_f32_16x16x32_bf16 v[44:47], v[150:153], v[206:209], v[44:47]
	v_mfma_f32_16x16x32_bf16 v[40:43], v[170:173], v[206:209], v[40:43]
	v_mfma_f32_16x16x32_bf16 v[28:31], v[150:153], v[214:217], v[28:31]
	v_mfma_f32_16x16x32_bf16 v[24:27], v[170:173], v[214:217], v[24:27]
	v_mfma_f32_16x16x32_bf16 v[12:15], v[150:153], v[222:225], v[12:15]
	v_mfma_f32_16x16x32_bf16 v[8:11], v[170:173], v[222:225], v[8:11]
	s_setprio 0
	s_setprio 3
	v_mfma_f32_16x16x32_bf16 v[52:55], v[174:177], v[190:193], v[52:55]
	v_mfma_f32_16x16x32_bf16 v[48:51], v[182:185], v[190:193], v[48:51]
	v_mfma_f32_16x16x32_bf16 v[36:39], v[174:177], v[198:201], v[36:39]
	v_mfma_f32_16x16x32_bf16 v[32:35], v[182:185], v[198:201], v[32:35]
	v_mfma_f32_16x16x32_bf16 v[20:23], v[174:177], v[210:213], v[20:23]
	v_mfma_f32_16x16x32_bf16 v[16:19], v[182:185], v[210:213], v[16:19]
	v_mfma_f32_16x16x32_bf16 v[4:7], v[174:177], v[218:221], v[4:7]
	v_mfma_f32_16x16x32_bf16 v[0:3], v[182:185], v[218:221], v[0:3]
	v_mfma_f32_16x16x32_bf16 v[52:55], v[178:181], v[194:197], v[52:55]
	v_mfma_f32_16x16x32_bf16 v[48:51], v[186:189], v[194:197], v[48:51]
	v_mfma_f32_16x16x32_bf16 v[36:39], v[178:181], v[206:209], v[36:39]
	v_mfma_f32_16x16x32_bf16 v[32:35], v[186:189], v[206:209], v[32:35]
	v_mfma_f32_16x16x32_bf16 v[20:23], v[178:181], v[214:217], v[20:23]
	v_mfma_f32_16x16x32_bf16 v[16:19], v[186:189], v[214:217], v[16:19]
	v_mfma_f32_16x16x32_bf16 v[4:7], v[178:181], v[222:225], v[4:7]
	v_mfma_f32_16x16x32_bf16 v[0:3], v[186:189], v[222:225], v[0:3]
	s_setprio 0
	s_barrier
	s_add_i32 s92, 0, 0x18000
	v_add_u32_e32 v165, s92, v156
	v_xor_b32_e32 v253, 64, v165
	s_add_i32 s93, 0, 0x1c000
	ds_read_b128 v[128:131], v165
	ds_read_b128 v[150:153], v253
	ds_read_b128 v[166:169], v165 offset:2048
	ds_read_b128 v[170:173], v253 offset:2048
	v_add_u32_e32 v165, s93, v156
	v_xor_b32_e32 v253, 64, v165
	ds_read_b128 v[174:177], v165
	ds_read_b128 v[178:181], v253
	ds_read_b128 v[182:185], v165 offset:2048
	ds_read_b128 v[186:189], v253 offset:2048
	v_lshl_add_u64 v[242:243], s[62:63], 0, v[132:133]
	s_mov_b32 m0, s68
	v_lshl_add_u64 v[244:245], s[62:63], 0, v[136:137]
	global_load_lds_dwordx4 v[242:243], off
	s_mov_b32 m0, s69
	s_nop 0
	global_load_lds_dwordx4 v[244:245], off
	s_add_u32 s62, s62, 0x104000
	s_addc_u32 s63, s63, 0
	s_mov_b32 m0, s70
	v_lshl_add_u64 v[234:235], s[62:63], 0, v[132:133]
	ds_read_b128 v[190:193], v160 offset:32768
	ds_read_b128 v[194:197], v250 offset:32768
	ds_read_b128 v[198:201], v160 offset:34816
	ds_read_b128 v[206:209], v250 offset:34816
	ds_read_b128 v[210:213], v160 offset:36864
	ds_read_b128 v[214:217], v250 offset:36864
	ds_read_b128 v[218:221], v160 offset:38912
	ds_read_b128 v[222:225], v250 offset:38912
	global_load_lds_dwordx4 v[234:235], off
	v_lshl_add_u64 v[234:235], s[62:63], 0, v[136:137]
	s_mov_b32 m0, s71
	s_nop 0
	global_load_lds_dwordx4 v[234:235], off
	s_waitcnt vmcnt(8)
	s_waitcnt lgkmcnt(0)
	s_barrier
; #define PG8_STAGE(bufoff, gbase, voff) do { _Pragma("unroll") for (int _i = 0; _i < 2; ++_i) \
;         __builtin_amdgcn_global_load_lds((const unsigned*)((const char*)(gbase) + (voff)[_i]), (LAS unsigned*)(lds + (bufoff) + ldsw + _i * 8192), 16, 0, 0); } while (0)
; #define PG8_LDA(dst, b, h) do { _Pragma("unroll") for (int m = 0; m < 4; ++m) _Pragma("unroll") for (int k = 0; k < 2; ++k) dst[m][k] = *(const LAS bf16x8*)(lds + PG8_SA(b, h) + aoff + m * 2048 + k * 1024); } while (0)
; #define PG8_MMA(ai, bj, At, Bt) do { __builtin_amdgcn_s_setprio(3); _Pragma("unroll") for (int m = 0; m < 4; ++m) _Pragma("unroll") for (int n = 0; n < 2; ++n) _Pragma("unroll") for (int k = 0; k < 2; ++k) \
;         acc[ai][bj][m][n] = __builtin_amdgcn_mfma_f32_16x16x32_bf16(Bt[n][k], At[m][k], acc[ai][bj][m][n], 0, 0, 0); __builtin_amdgcn_s_setprio(0); } while (0)
; #define PG8_WAIT_V(n) asm volatile("s_waitcnt vmcnt(" #n ")" ::: "memory")
; #define PG8_WAIT_L(n) asm volatile("s_waitcnt lgkmcnt(" #n ")" ::: "memory")
; #define PG8_BAR __builtin_amdgcn_s_barrier()
; #define PG8_SCHED __builtin_amdgcn_sched_barrier(0)
; template <class Epi, class Sched, bool ALIGN_EPI = false, bool SP2 = false>
; __device__ __forceinline__ void gemm_phase(LAS unsigned char* lds, const Gemm g, const Sched& S, const Epi& E) {
;     ...
;         for (int t = 0; t < nt; t += 2) {
;     ...
;             PG8_WAIT_V(8); PG8_WAIT_L(0); PG8_BAR; PG8_MMA(0, 0, At, B0); PG8_MMA(0, 1, At, B1); PG8_BAR; PG8_SCHED;
;             PG8_LDA(At, 1, 1); PG8_STAGE(PG8_SB(1, 0), b3, voffB); PG8_STAGE(PG8_SB(1, 1), b3 + hsB, voffB); PG8_STAGE(PG8_SA(1, 0), a3, voffA);
;             PG8_WAIT_V(8); PG8_WAIT_L(0); PG8_BAR; PG8_MMA(1, 0, At, B0); PG8_MMA(1, 1, At, B1); PG8_BAR; PG8_SCHED;
	s_setprio 3
	s_waitcnt lgkmcnt(0)
	v_mfma_f32_16x16x32_bf16 v[124:127], v[128:131], v[190:193], v[124:127]
	v_mfma_f32_16x16x32_bf16 v[120:123], v[166:169], v[190:193], v[120:123]
	v_mfma_f32_16x16x32_bf16 v[108:111], v[128:131], v[198:201], v[108:111]
	v_mfma_f32_16x16x32_bf16 v[104:107], v[166:169], v[198:201], v[104:107]
	v_mfma_f32_16x16x32_bf16 v[92:95], v[128:131], v[210:213], v[92:95]
	v_mfma_f32_16x16x32_bf16 v[88:91], v[166:169], v[210:213], v[88:91]
	v_mfma_f32_16x16x32_bf16 v[76:79], v[128:131], v[218:221], v[76:79]
	v_mfma_f32_16x16x32_bf16 v[72:75], v[166:169], v[218:221], v[72:75]
	v_mfma_f32_16x16x32_bf16 v[124:127], v[150:153], v[194:197], v[124:127]
	v_mfma_f32_16x16x32_bf16 v[120:123], v[170:173], v[194:197], v[120:123]
	v_mfma_f32_16x16x32_bf16 v[108:111], v[150:153], v[206:209], v[108:111]
	v_mfma_f32_16x16x32_bf16 v[104:107], v[170:173], v[206:209], v[104:107]
	v_mfma_f32_16x16x32_bf16 v[92:95], v[150:153], v[214:217], v[92:95]
	v_mfma_f32_16x16x32_bf16 v[88:91], v[170:173], v[214:217], v[88:91]
	v_mfma_f32_16x16x32_bf16 v[76:79], v[150:153], v[222:225], v[76:79]
	v_mfma_f32_16x16x32_bf16 v[72:75], v[170:173], v[222:225], v[72:75]
	s_setprio 0
	s_setprio 3
	v_mfma_f32_16x16x32_bf16 v[116:119], v[174:177], v[190:193], v[116:119]
	v_mfma_f32_16x16x32_bf16 v[112:115], v[182:185], v[190:193], v[112:115]
	v_mfma_f32_16x16x32_bf16 v[100:103], v[174:177], v[198:201], v[100:103]
	v_mfma_f32_16x16x32_bf16 v[96:99], v[182:185], v[198:201], v[96:99]
	v_mfma_f32_16x16x32_bf16 v[84:87], v[174:177], v[210:213], v[84:87]
	v_mfma_f32_16x16x32_bf16 v[80:83], v[182:185], v[210:213], v[80:83]
	v_mfma_f32_16x16x32_bf16 v[68:71], v[174:177], v[218:221], v[68:71]
	v_mfma_f32_16x16x32_bf16 v[64:67], v[182:185], v[218:221], v[64:67]
	v_mfma_f32_16x16x32_bf16 v[116:119], v[178:181], v[194:197], v[116:119]
	v_mfma_f32_16x16x32_bf16 v[112:115], v[186:189], v[194:197], v[112:115]
	v_mfma_f32_16x16x32_bf16 v[100:103], v[178:181], v[206:209], v[100:103]
	v_mfma_f32_16x16x32_bf16 v[96:99], v[186:189], v[206:209], v[96:99]
	v_mfma_f32_16x16x32_bf16 v[84:87], v[178:181], v[214:217], v[84:87]
	v_mfma_f32_16x16x32_bf16 v[80:83], v[186:189], v[214:217], v[80:83]
	v_mfma_f32_16x16x32_bf16 v[68:71], v[178:181], v[222:225], v[68:71]
	v_mfma_f32_16x16x32_bf16 v[64:67], v[186:189], v[222:225], v[64:67]
	s_setprio 0
	s_barrier
	s_add_i32 s62, s92, s67
	v_lshl_add_u64 v[226:227], v[226:227], 0, s[46:47]
	s_mov_b32 m0, s62
	ds_read_b128 v[190:193], v160 offset:49152
	ds_read_b128 v[194:197], v250 offset:49152
	ds_read_b128 v[198:201], v160 offset:51200
	ds_read_b128 v[206:209], v250 offset:51200
	ds_read_b128 v[210:213], v160 offset:53248
	ds_read_b128 v[214:217], v250 offset:53248
	ds_read_b128 v[218:221], v160 offset:55296
	ds_read_b128 v[222:225], v250 offset:55296
	global_load_lds_dwordx4 v[226:227], off
	s_add_i32 m0, s62, 0x2000
	s_add_u32 s6, s6, 0x41080
	v_lshl_add_u64 v[226:227], v[228:229], 0, s[46:47]
	s_addc_u32 s7, s7, 0
	s_add_i32 s62, s93, s67
	global_load_lds_dwordx4 v[226:227], off
	v_lshl_add_u64 v[226:227], s[6:7], 0, v[134:135]
	s_mov_b32 m0, s62
	s_nop 0
	global_load_lds_dwordx4 v[226:227], off
	v_lshl_add_u64 v[226:227], s[6:7], 0, v[138:139]
	s_add_i32 m0, s62, 0x2000
	s_nop 0
	global_load_lds_dwordx4 v[226:227], off
	s_waitcnt vmcnt(6)
	s_waitcnt lgkmcnt(0)
	s_barrier
	s_setprio 3
	s_waitcnt lgkmcnt(0)
	v_mfma_f32_16x16x32_bf16 v[60:63], v[128:131], v[190:193], v[60:63]
	v_mfma_f32_16x16x32_bf16 v[56:59], v[166:169], v[190:193], v[56:59]
	v_mfma_f32_16x16x32_bf16 v[44:47], v[128:131], v[198:201], v[44:47]
	v_mfma_f32_16x16x32_bf16 v[40:43], v[166:169], v[198:201], v[40:43]
	v_mfma_f32_16x16x32_bf16 v[28:31], v[128:131], v[210:213], v[28:31]
	v_mfma_f32_16x16x32_bf16 v[24:27], v[166:169], v[210:213], v[24:27]
	v_mfma_f32_16x16x32_bf16 v[12:15], v[128:131], v[218:221], v[12:15]
	v_mfma_f32_16x16x32_bf16 v[8:11], v[166:169], v[218:221], v[8:11]
	v_mfma_f32_16x16x32_bf16 v[60:63], v[150:153], v[194:197], v[60:63]
	v_mfma_f32_16x16x32_bf16 v[56:59], v[170:173], v[194:197], v[56:59]
	v_mfma_f32_16x16x32_bf16 v[44:47], v[150:153], v[206:209], v[44:47]
	v_mfma_f32_16x16x32_bf16 v[40:43], v[170:173], v[206:209], v[40:43]
	v_mfma_f32_16x16x32_bf16 v[28:31], v[150:153], v[214:217], v[28:31]
	v_mfma_f32_16x16x32_bf16 v[24:27], v[170:173], v[214:217], v[24:27]
	v_mfma_f32_16x16x32_bf16 v[12:15], v[150:153], v[222:225], v[12:15]
	v_mfma_f32_16x16x32_bf16 v[8:11], v[170:173], v[222:225], v[8:11]
	s_setprio 0
	s_setprio 3
	v_mfma_f32_16x16x32_bf16 v[52:55], v[174:177], v[190:193], v[52:55]
	v_mfma_f32_16x16x32_bf16 v[48:51], v[182:185], v[190:193], v[48:51]
	v_mfma_f32_16x16x32_bf16 v[36:39], v[174:177], v[198:201], v[36:39]
	v_mfma_f32_16x16x32_bf16 v[32:35], v[182:185], v[198:201], v[32:35]
	v_mfma_f32_16x16x32_bf16 v[20:23], v[174:177], v[210:213], v[20:23]
	v_mfma_f32_16x16x32_bf16 v[16:19], v[182:185], v[210:213], v[16:19]
	v_mfma_f32_16x16x32_bf16 v[4:7], v[174:177], v[218:221], v[4:7]
	v_mfma_f32_16x16x32_bf16 v[0:3], v[182:185], v[218:221], v[0:3]
	v_mfma_f32_16x16x32_bf16 v[52:55], v[178:181], v[194:197], v[52:55]
	v_mfma_f32_16x16x32_bf16 v[48:51], v[186:189], v[194:197], v[48:51]
	v_mfma_f32_16x16x32_bf16 v[36:39], v[178:181], v[206:209], v[36:39]
	v_mfma_f32_16x16x32_bf16 v[32:35], v[186:189], v[206:209], v[32:35]
	v_mfma_f32_16x16x32_bf16 v[20:23], v[178:181], v[214:217], v[20:23]
	v_mfma_f32_16x16x32_bf16 v[16:19], v[186:189], v[214:217], v[16:19]
	v_mfma_f32_16x16x32_bf16 v[4:7], v[178:181], v[222:225], v[4:7]
	v_mfma_f32_16x16x32_bf16 v[0:3], v[186:189], v[222:225], v[0:3]
	s_setprio 0
	s_barrier
	s_add_i32 s91, s91, 2
	s_add_u32 s4, s4, 0x100
	s_addc_u32 s5, s5, 0
	s_add_u32 s89, s89, 0x100
	s_addc_u32 s90, s90, 0
	s_cmp_gt_u32 s91, 61
	s_cbranch_scc0 .LBB0_64
	s_and_b64 vcc, exec, s[50:51]
	s_cbranch_vccz .LBB0_67
	s_barrier

; #define PG8_STAGE(bufoff, gbase, voff) do { _Pragma("unroll") for (int _i = 0; _i < 2; ++_i) \
;         __builtin_amdgcn_global_load_lds((const unsigned*)((const char*)(gbase) + (voff)[_i]), (LAS unsigned*)(lds + (bufoff) + ldsw + _i * 8192), 16, 0, 0); } while (0)
; #define PG8_LDA(dst, b, h) do { _Pragma("unroll") for (int m = 0; m < 4; ++m) _Pragma("unroll") for (int k = 0; k < 2; ++k) dst[m][k] = *(const LAS bf16x8*)(lds + PG8_SA(b, h) + aoff + m * 2048 + k * 1024); } while (0)
; #define PG8_LDB(dst, b, h) do { _Pragma("unroll") for (int n = 0; n < 2; ++n) _Pragma("unroll") for (int k = 0; k < 2; ++k) dst[n][k] = *(const LAS bf16x8*)(lds + PG8_SB(b, h) + boff + n * 2048 + k * 1024); } while (0)
; #define PG8_MMA(ai, bj, At, Bt) do { __builtin_amdgcn_s_setprio(3); _Pragma("unroll") for (int m = 0; m < 4; ++m) _Pragma("unroll") for (int n = 0; n < 2; ++n) _Pragma("unroll") for (int k = 0; k < 2; ++k) \
;         acc[ai][bj][m][n] = __builtin_amdgcn_mfma_f32_16x16x32_bf16(Bt[n][k], At[m][k], acc[ai][bj][m][n], 0, 0, 0); __builtin_amdgcn_s_setprio(0); } while (0)
; #define PG8_WAIT_V(n) asm volatile("s_waitcnt vmcnt(" #n ")" ::: "memory")
; #define PG8_WAIT_L(n) asm volatile("s_waitcnt lgkmcnt(" #n ")" ::: "memory")
; #define PG8_BAR __builtin_amdgcn_s_barrier()
; #define PG8_SCHED __builtin_amdgcn_sched_barrier(0)
; template <class Epi, class Sched, bool ALIGN_EPI = false, bool SP2 = false>
; __device__ __forceinline__ void gemm_phase(LAS unsigned char* lds, const Gemm g, const Sched& S, const Epi& E) {
;     ...
;             PG8_LDB(B0, 0, 0); PG8_LDB(B1, 0, 1); PG8_SCHED; PG8_LDA(At, 0, 0); PG8_STAGE(PG8_SA(1, 1), a1 + hsA, voffA);
;             PG8_WAIT_V(8); PG8_WAIT_L(0); PG8_BAR; PG8_MMA(0, 0, At, B0); PG8_MMA(0, 1, At, B1); PG8_BAR; PG8_SCHED;
;             PG8_LDA(At, 0, 1); PG8_STAGE(PG8_SB(0, 0), b2, voffB); PG8_STAGE(PG8_SB(0, 1), b2 + hsB, voffB); PG8_STAGE(PG8_SA(0, 0), a2, voffA);
;             PG8_WAIT_V(8); PG8_WAIT_L(0); PG8_BAR; PG8_MMA(1, 0, At, B0); PG8_MMA(1, 1, At, B1); PG8_BAR; PG8_SCHED;
.LBB0_234:
	v_add_u32_e32 v1, s88, v194
	v_xor_b32_e32 v253, 64, v1
	ds_read_b128 v[84:87], v1
	ds_read_b128 v[96:99], v253
	ds_read_b128 v[140:143], v1 offset:2048
	ds_read_b128 v[144:147], v253 offset:2048
	v_add_u32_e32 v1, s89, v194
	v_xor_b32_e32 v253, 64, v1
	s_add_u32 s4, s64, s66
	ds_read_b128 v[152:155], v1
	ds_read_b128 v[156:159], v253
	ds_read_b128 v[160:163], v1 offset:2048
	ds_read_b128 v[182:185], v253 offset:2048
	s_addc_u32 s5, s65, s67
	s_add_u32 s4, s4, 0x100
	s_addc_u32 s5, s5, 0
	s_add_u32 s96, s93, s66
	s_addc_u32 s97, s94, s67
	s_cmpk_eq_i32 s66, 0x1f00
	s_cselect_b32 s9, s59, s5
	s_cselect_b32 s8, s91, s4
	s_cselect_b32 s5, s61, s97
	s_cselect_b32 s4, s60, s96
	s_sub_u32 s100, s66, 0x100000
	s_subb_u32 s101, s67, 0
	v_lshl_add_u64 v[242:243], v[148:149], 0, s[100:101]
	s_mov_b32 m0, s81
	v_lshl_add_u64 v[244:245], v[150:151], 0, s[100:101]
	global_load_lds_dwordx4 v[242:243], off
	s_mov_b32 m0, s82
	s_nop 0
	global_load_lds_dwordx4 v[244:245], off
	v_lshl_add_u64 v[2:3], v[148:149], 0, s[66:67]
	s_add_i32 m0, s41, 0xc000
	ds_read_b128 v[186:189], v198
	ds_read_b128 v[208:211], v250
	ds_read_b128 v[212:215], v198 offset:2048
	ds_read_b128 v[216:219], v250 offset:2048
	ds_read_b128 v[220:223], v198 offset:4096
	ds_read_b128 v[224:227], v250 offset:4096
	ds_read_b128 v[228:231], v198 offset:6144
	ds_read_b128 v[232:235], v250 offset:6144
	global_load_lds_dwordx4 v[2:3], off
	v_lshl_add_u64 v[2:3], v[150:151], 0, s[66:67]
	s_add_i32 m0, s41, 0xe000
	s_nop 0
	global_load_lds_dwordx4 v[2:3], off
	s_waitcnt vmcnt(8)
	s_waitcnt lgkmcnt(0)
	s_barrier
	s_setprio 3
	s_waitcnt lgkmcnt(0)
	v_mfma_f32_16x16x32_bf16 v[136:139], v[84:87], v[186:189], v[136:139]
	v_mfma_f32_16x16x32_bf16 v[132:135], v[140:143], v[186:189], v[132:135]
	v_mfma_f32_16x16x32_bf16 v[120:123], v[84:87], v[212:215], v[120:123]
	v_mfma_f32_16x16x32_bf16 v[116:119], v[140:143], v[212:215], v[116:119]
	v_mfma_f32_16x16x32_bf16 v[104:107], v[84:87], v[220:223], v[104:107]
	v_mfma_f32_16x16x32_bf16 v[100:103], v[140:143], v[220:223], v[100:103]
	v_mfma_f32_16x16x32_bf16 v[80:83], v[84:87], v[228:231], v[80:83]
	v_mfma_f32_16x16x32_bf16 v[76:79], v[140:143], v[228:231], v[76:79]
	v_mfma_f32_16x16x32_bf16 v[136:139], v[96:99], v[208:211], v[136:139]
	v_mfma_f32_16x16x32_bf16 v[132:135], v[144:147], v[208:211], v[132:135]
	v_mfma_f32_16x16x32_bf16 v[120:123], v[96:99], v[216:219], v[120:123]
	v_mfma_f32_16x16x32_bf16 v[116:119], v[144:147], v[216:219], v[116:119]
	v_mfma_f32_16x16x32_bf16 v[104:107], v[96:99], v[224:227], v[104:107]
	v_mfma_f32_16x16x32_bf16 v[100:103], v[144:147], v[224:227], v[100:103]
	v_mfma_f32_16x16x32_bf16 v[80:83], v[96:99], v[232:235], v[80:83]
	v_mfma_f32_16x16x32_bf16 v[76:79], v[144:147], v[232:235], v[76:79]
	s_setprio 0
	s_setprio 3
	v_mfma_f32_16x16x32_bf16 v[128:131], v[152:155], v[186:189], v[128:131]
	v_mfma_f32_16x16x32_bf16 v[124:127], v[160:163], v[186:189], v[124:127]
	v_mfma_f32_16x16x32_bf16 v[112:115], v[152:155], v[212:215], v[112:115]
	v_mfma_f32_16x16x32_bf16 v[108:111], v[160:163], v[212:215], v[108:111]
	v_mfma_f32_16x16x32_bf16 v[92:95], v[152:155], v[220:223], v[92:95]
	v_mfma_f32_16x16x32_bf16 v[88:91], v[160:163], v[220:223], v[88:91]
	v_mfma_f32_16x16x32_bf16 v[72:75], v[152:155], v[228:231], v[72:75]
	v_mfma_f32_16x16x32_bf16 v[68:71], v[160:163], v[228:231], v[68:71]
	v_mfma_f32_16x16x32_bf16 v[128:131], v[156:159], v[208:211], v[128:131]
	v_mfma_f32_16x16x32_bf16 v[124:127], v[182:185], v[208:211], v[124:127]
	v_mfma_f32_16x16x32_bf16 v[112:115], v[156:159], v[216:219], v[112:115]
	v_mfma_f32_16x16x32_bf16 v[108:111], v[182:185], v[216:219], v[108:111]
	v_mfma_f32_16x16x32_bf16 v[92:95], v[156:159], v[224:227], v[92:95]
	v_mfma_f32_16x16x32_bf16 v[88:91], v[182:185], v[224:227], v[88:91]
	v_mfma_f32_16x16x32_bf16 v[72:75], v[156:159], v[232:235], v[72:75]
	v_mfma_f32_16x16x32_bf16 v[68:71], v[182:185], v[232:235], v[68:71]
	s_setprio 0
	s_barrier
	s_add_i32 s96, s88, s31
	v_lshl_add_u64 v[190:191], s[4:5], 0, v[166:167]
	s_mov_b32 m0, s96
	ds_read_b128 v[186:189], v198 offset:16384
	ds_read_b128 v[208:211], v250 offset:16384
	ds_read_b128 v[212:215], v198 offset:18432
	ds_read_b128 v[216:219], v250 offset:18432
	ds_read_b128 v[220:223], v198 offset:20480
	ds_read_b128 v[224:227], v250 offset:20480
	ds_read_b128 v[228:231], v198 offset:22528
	ds_read_b128 v[232:235], v250 offset:22528
	global_load_lds_dwordx4 v[190:191], off
	s_add_i32 m0, s96, 0x2000
	s_add_u32 s96, s4, 0x104000
	v_lshl_add_u64 v[236:237], s[4:5], 0, v[170:171]
	s_addc_u32 s97, s5, 0
	s_add_i32 s98, s89, s31
	global_load_lds_dwordx4 v[236:237], off
	v_lshl_add_u64 v[2:3], s[96:97], 0, v[166:167]
	s_mov_b32 m0, s98
	s_nop 0
	global_load_lds_dwordx4 v[2:3], off
	v_lshl_add_u64 v[2:3], s[96:97], 0, v[170:171]
	s_add_i32 m0, s98, 0x2000
	s_nop 0
	global_load_lds_dwordx4 v[2:3], off
	s_waitcnt vmcnt(6)
	s_waitcnt lgkmcnt(0)
	s_barrier
; #define PG8_STAGE(bufoff, gbase, voff) do { _Pragma("unroll") for (int _i = 0; _i < 2; ++_i) \
;         __builtin_amdgcn_global_load_lds((const unsigned*)((const char*)(gbase) + (voff)[_i]), (LAS unsigned*)(lds + (bufoff) + ldsw + _i * 8192), 16, 0, 0); } while (0)
; #define PG8_LDA(dst, b, h) do { _Pragma("unroll") for (int m = 0; m < 4; ++m) _Pragma("unroll") for (int k = 0; k < 2; ++k) dst[m][k] = *(const LAS bf16x8*)(lds + PG8_SA(b, h) + aoff + m * 2048 + k * 1024); } while (0)
; #define PG8_LDB(dst, b, h) do { _Pragma("unroll") for (int n = 0; n < 2; ++n) _Pragma("unroll") for (int k = 0; k < 2; ++k) dst[n][k] = *(const LAS bf16x8*)(lds + PG8_SB(b, h) + boff + n * 2048 + k * 1024); } while (0)
; #define PG8_MMA(ai, bj, At, Bt) do { __builtin_amdgcn_s_setprio(3); _Pragma("unroll") for (int m = 0; m < 4; ++m) _Pragma("unroll") for (int n = 0; n < 2; ++n) _Pragma("unroll") for (int k = 0; k < 2; ++k) \
;         acc[ai][bj][m][n] = __builtin_amdgcn_mfma_f32_16x16x32_bf16(Bt[n][k], At[m][k], acc[ai][bj][m][n], 0, 0, 0); __builtin_amdgcn_s_setprio(0); } while (0)
; #define PG8_WAIT_V(n) asm volatile("s_waitcnt vmcnt(" #n ")" ::: "memory")
; #define PG8_WAIT_L(n) asm volatile("s_waitcnt lgkmcnt(" #n ")" ::: "memory")
; #define PG8_BAR __builtin_amdgcn_s_barrier()
; #define PG8_SCHED __builtin_amdgcn_sched_barrier(0)
; template <class Epi, class Sched, bool ALIGN_EPI = false, bool SP2 = false>
; __device__ __forceinline__ void gemm_phase(LAS unsigned char* lds, const Gemm g, const Sched& S, const Epi& E) {
;     ...
;             PG8_WAIT_V(8); PG8_WAIT_L(0); PG8_BAR; PG8_MMA(1, 0, At, B0); PG8_MMA(1, 1, At, B1); PG8_BAR; PG8_SCHED;
;             PG8_LDB(B0, 1, 0); PG8_LDB(B1, 1, 1); PG8_SCHED; PG8_LDA(At, 1, 0); PG8_STAGE(PG8_SA(0, 1), a2 + hsA, voffA);
;             PG8_WAIT_V(8); PG8_WAIT_L(0); PG8_BAR; PG8_MMA(0, 0, At, B0); PG8_MMA(0, 1, At, B1); PG8_BAR; PG8_SCHED;
	s_setprio 3
	s_waitcnt lgkmcnt(0)
	v_mfma_f32_16x16x32_bf16 v[64:67], v[84:87], v[186:189], v[64:67]
	v_mfma_f32_16x16x32_bf16 v[60:63], v[140:143], v[186:189], v[60:63]
	v_mfma_f32_16x16x32_bf16 v[48:51], v[84:87], v[212:215], v[48:51]
	v_mfma_f32_16x16x32_bf16 v[44:47], v[140:143], v[212:215], v[44:47]
	v_mfma_f32_16x16x32_bf16 v[32:35], v[84:87], v[220:223], v[32:35]
	v_mfma_f32_16x16x32_bf16 v[28:31], v[140:143], v[220:223], v[28:31]
	v_mfma_f32_16x16x32_bf16 v[16:19], v[84:87], v[228:231], v[16:19]
	v_mfma_f32_16x16x32_bf16 v[12:15], v[140:143], v[228:231], v[12:15]
	v_mfma_f32_16x16x32_bf16 v[64:67], v[96:99], v[208:211], v[64:67]
	v_mfma_f32_16x16x32_bf16 v[60:63], v[144:147], v[208:211], v[60:63]
	v_mfma_f32_16x16x32_bf16 v[48:51], v[96:99], v[216:219], v[48:51]
	v_mfma_f32_16x16x32_bf16 v[44:47], v[144:147], v[216:219], v[44:47]
	v_mfma_f32_16x16x32_bf16 v[32:35], v[96:99], v[224:227], v[32:35]
	v_mfma_f32_16x16x32_bf16 v[28:31], v[144:147], v[224:227], v[28:31]
	v_mfma_f32_16x16x32_bf16 v[16:19], v[96:99], v[232:235], v[16:19]
	v_mfma_f32_16x16x32_bf16 v[12:15], v[144:147], v[232:235], v[12:15]
	s_setprio 0
	s_setprio 3
	v_mfma_f32_16x16x32_bf16 v[56:59], v[152:155], v[186:189], v[56:59]
	v_mfma_f32_16x16x32_bf16 v[52:55], v[160:163], v[186:189], v[52:55]
	v_mfma_f32_16x16x32_bf16 v[40:43], v[152:155], v[212:215], v[40:43]
	v_mfma_f32_16x16x32_bf16 v[36:39], v[160:163], v[212:215], v[36:39]
	v_mfma_f32_16x16x32_bf16 v[24:27], v[152:155], v[220:223], v[24:27]
	v_mfma_f32_16x16x32_bf16 v[20:23], v[160:163], v[220:223], v[20:23]
	v_mfma_f32_16x16x32_bf16 v[8:11], v[152:155], v[228:231], v[8:11]
	v_mfma_f32_16x16x32_bf16 v[2:5], v[160:163], v[228:231], v[4:7]
	v_mfma_f32_16x16x32_bf16 v[56:59], v[156:159], v[208:211], v[56:59]
	v_mfma_f32_16x16x32_bf16 v[52:55], v[182:185], v[208:211], v[52:55]
	v_mfma_f32_16x16x32_bf16 v[40:43], v[156:159], v[216:219], v[40:43]
	v_mfma_f32_16x16x32_bf16 v[36:39], v[182:185], v[216:219], v[36:39]
	v_mfma_f32_16x16x32_bf16 v[24:27], v[156:159], v[224:227], v[24:27]
	v_mfma_f32_16x16x32_bf16 v[20:23], v[182:185], v[224:227], v[20:23]
	v_mfma_f32_16x16x32_bf16 v[8:11], v[156:159], v[232:235], v[8:11]
	v_mfma_f32_16x16x32_bf16 v[2:5], v[182:185], v[232:235], v[2:5]
	s_setprio 0
	s_barrier
	s_add_i32 s96, 0, 0x18000
	v_add_u32_e32 v1, s96, v194
	v_xor_b32_e32 v253, 64, v1
	s_add_i32 s97, 0, 0x1c000
	ds_read_b128 v[84:87], v1
	ds_read_b128 v[96:99], v253
	ds_read_b128 v[140:143], v1 offset:2048
	ds_read_b128 v[144:147], v253 offset:2048
	v_add_u32_e32 v1, s97, v194
	v_xor_b32_e32 v253, 64, v1
	ds_read_b128 v[152:155], v1
	ds_read_b128 v[156:159], v253
	ds_read_b128 v[160:163], v1 offset:2048
	ds_read_b128 v[182:185], v253 offset:2048
	v_lshl_add_u64 v[242:243], s[8:9], 0, v[164:165]
	s_mov_b32 m0, s41
	v_lshl_add_u64 v[244:245], s[8:9], 0, v[168:169]
	global_load_lds_dwordx4 v[242:243], off
	s_mov_b32 m0, s68
	s_nop 0
	global_load_lds_dwordx4 v[244:245], off
	s_add_u32 s8, s8, 0x100000
	s_addc_u32 s9, s9, 0
	s_mov_b32 m0, s69
	v_lshl_add_u64 v[6:7], s[8:9], 0, v[164:165]
	ds_read_b128 v[186:189], v198 offset:32768
	ds_read_b128 v[208:211], v250 offset:32768
	ds_read_b128 v[212:215], v198 offset:34816
	ds_read_b128 v[216:219], v250 offset:34816
	ds_read_b128 v[220:223], v198 offset:36864
	ds_read_b128 v[224:227], v250 offset:36864
	ds_read_b128 v[228:231], v198 offset:38912
	ds_read_b128 v[232:235], v250 offset:38912
	global_load_lds_dwordx4 v[6:7], off
	v_lshl_add_u64 v[6:7], s[8:9], 0, v[168:169]
	s_mov_b32 m0, s70
	s_nop 0
	global_load_lds_dwordx4 v[6:7], off
	s_waitcnt vmcnt(8)
	s_waitcnt lgkmcnt(0)
	s_barrier
; #define PG8_STAGE(bufoff, gbase, voff) do { _Pragma("unroll") for (int _i = 0; _i < 2; ++_i) \
;         __builtin_amdgcn_global_load_lds((const unsigned*)((const char*)(gbase) + (voff)[_i]), (LAS unsigned*)(lds + (bufoff) + ldsw + _i * 8192), 16, 0, 0); } while (0)
; #define PG8_LDA(dst, b, h) do { _Pragma("unroll") for (int m = 0; m < 4; ++m) _Pragma("unroll") for (int k = 0; k < 2; ++k) dst[m][k] = *(const LAS bf16x8*)(lds + PG8_SA(b, h) + aoff + m * 2048 + k * 1024); } while (0)
; #define PG8_MMA(ai, bj, At, Bt) do { __builtin_amdgcn_s_setprio(3); _Pragma("unroll") for (int m = 0; m < 4; ++m) _Pragma("unroll") for (int n = 0; n < 2; ++n) _Pragma("unroll") for (int k = 0; k < 2; ++k) \
;         acc[ai][bj][m][n] = __builtin_amdgcn_mfma_f32_16x16x32_bf16(Bt[n][k], At[m][k], acc[ai][bj][m][n], 0, 0, 0); __builtin_amdgcn_s_setprio(0); } while (0)
; #define PG8_WAIT_V(n) asm volatile("s_waitcnt vmcnt(" #n ")" ::: "memory")
; #define PG8_WAIT_L(n) asm volatile("s_waitcnt lgkmcnt(" #n ")" ::: "memory")
; #define PG8_BAR __builtin_amdgcn_s_barrier()
; #define PG8_SCHED __builtin_amdgcn_sched_barrier(0)
; template <class Epi, class Sched, bool ALIGN_EPI = false, bool SP2 = false>
; __device__ __forceinline__ void gemm_phase(LAS unsigned char* lds, const Gemm g, const Sched& S, const Epi& E) {
;     ...
;         for (int t = 0; t < nt; t += 2) {
;     ...
;             PG8_WAIT_V(8); PG8_WAIT_L(0); PG8_BAR; PG8_MMA(0, 0, At, B0); PG8_MMA(0, 1, At, B1); PG8_BAR; PG8_SCHED;
;             PG8_LDA(At, 1, 1); PG8_STAGE(PG8_SB(1, 0), b3, voffB); PG8_STAGE(PG8_SB(1, 1), b3 + hsB, voffB); PG8_STAGE(PG8_SA(1, 0), a3, voffA);
;             PG8_WAIT_V(8); PG8_WAIT_L(0); PG8_BAR; PG8_MMA(1, 0, At, B0); PG8_MMA(1, 1, At, B1); PG8_BAR; PG8_SCHED;
	s_setprio 3
	s_waitcnt lgkmcnt(0)
	v_mfma_f32_16x16x32_bf16 v[136:139], v[84:87], v[186:189], v[136:139]
	v_mfma_f32_16x16x32_bf16 v[132:135], v[140:143], v[186:189], v[132:135]
	v_mfma_f32_16x16x32_bf16 v[120:123], v[84:87], v[212:215], v[120:123]
	v_mfma_f32_16x16x32_bf16 v[116:119], v[140:143], v[212:215], v[116:119]
	v_mfma_f32_16x16x32_bf16 v[104:107], v[84:87], v[220:223], v[104:107]
	v_mfma_f32_16x16x32_bf16 v[100:103], v[140:143], v[220:223], v[100:103]
	v_mfma_f32_16x16x32_bf16 v[80:83], v[84:87], v[228:231], v[80:83]
	v_mfma_f32_16x16x32_bf16 v[76:79], v[140:143], v[228:231], v[76:79]
	v_mfma_f32_16x16x32_bf16 v[136:139], v[96:99], v[208:211], v[136:139]
	v_mfma_f32_16x16x32_bf16 v[132:135], v[144:147], v[208:211], v[132:135]
	v_mfma_f32_16x16x32_bf16 v[120:123], v[96:99], v[216:219], v[120:123]
	v_mfma_f32_16x16x32_bf16 v[116:119], v[144:147], v[216:219], v[116:119]
	v_mfma_f32_16x16x32_bf16 v[104:107], v[96:99], v[224:227], v[104:107]
	v_mfma_f32_16x16x32_bf16 v[100:103], v[144:147], v[224:227], v[100:103]
	v_mfma_f32_16x16x32_bf16 v[80:83], v[96:99], v[232:235], v[80:83]
	v_mfma_f32_16x16x32_bf16 v[76:79], v[144:147], v[232:235], v[76:79]
	s_setprio 0
	s_setprio 3
	v_mfma_f32_16x16x32_bf16 v[128:131], v[152:155], v[186:189], v[128:131]
	v_mfma_f32_16x16x32_bf16 v[124:127], v[160:163], v[186:189], v[124:127]
	v_mfma_f32_16x16x32_bf16 v[112:115], v[152:155], v[212:215], v[112:115]
	v_mfma_f32_16x16x32_bf16 v[108:111], v[160:163], v[212:215], v[108:111]
	v_mfma_f32_16x16x32_bf16 v[92:95], v[152:155], v[220:223], v[92:95]
	v_mfma_f32_16x16x32_bf16 v[88:91], v[160:163], v[220:223], v[88:91]
	v_mfma_f32_16x16x32_bf16 v[72:75], v[152:155], v[228:231], v[72:75]
	v_mfma_f32_16x16x32_bf16 v[68:71], v[160:163], v[228:231], v[68:71]
	v_mfma_f32_16x16x32_bf16 v[128:131], v[156:159], v[208:211], v[128:131]
	v_mfma_f32_16x16x32_bf16 v[124:127], v[182:185], v[208:211], v[124:127]
	v_mfma_f32_16x16x32_bf16 v[112:115], v[156:159], v[216:219], v[112:115]
	v_mfma_f32_16x16x32_bf16 v[108:111], v[182:185], v[216:219], v[108:111]
	v_mfma_f32_16x16x32_bf16 v[92:95], v[156:159], v[224:227], v[92:95]
	v_mfma_f32_16x16x32_bf16 v[88:91], v[182:185], v[224:227], v[88:91]
	v_mfma_f32_16x16x32_bf16 v[72:75], v[156:159], v[232:235], v[72:75]
	v_mfma_f32_16x16x32_bf16 v[68:71], v[182:185], v[232:235], v[68:71]
	s_setprio 0
	s_barrier
	s_add_i32 s8, s96, s31
	v_lshl_add_u64 v[6:7], v[190:191], 0, s[24:25]
	s_mov_b32 m0, s8
	ds_read_b128 v[186:189], v198 offset:49152
	ds_read_b128 v[208:211], v250 offset:49152
	ds_read_b128 v[212:215], v198 offset:51200
	ds_read_b128 v[216:219], v250 offset:51200
	ds_read_b128 v[220:223], v198 offset:53248
	ds_read_b128 v[224:227], v250 offset:53248
	ds_read_b128 v[228:231], v198 offset:55296
	ds_read_b128 v[232:235], v250 offset:55296
	global_load_lds_dwordx4 v[6:7], off
	s_add_i32 m0, s8, 0x2000
	s_add_u32 s4, s4, 0x104080
	v_lshl_add_u64 v[6:7], v[236:237], 0, s[24:25]
	s_addc_u32 s5, s5, 0
	s_add_i32 s8, s97, s31
	global_load_lds_dwordx4 v[6:7], off
	v_lshl_add_u64 v[6:7], s[4:5], 0, v[166:167]
	s_mov_b32 m0, s8
	s_nop 0
	global_load_lds_dwordx4 v[6:7], off
	v_lshl_add_u64 v[6:7], s[4:5], 0, v[170:171]
	s_add_i32 m0, s8, 0x2000
	s_nop 0
	global_load_lds_dwordx4 v[6:7], off
	s_waitcnt vmcnt(6)
	s_waitcnt lgkmcnt(0)
	s_barrier
	s_setprio 3
	s_waitcnt lgkmcnt(0)
	v_mfma_f32_16x16x32_bf16 v[64:67], v[84:87], v[186:189], v[64:67]
	v_mfma_f32_16x16x32_bf16 v[60:63], v[140:143], v[186:189], v[60:63]
	v_mfma_f32_16x16x32_bf16 v[48:51], v[84:87], v[212:215], v[48:51]
	v_mfma_f32_16x16x32_bf16 v[44:47], v[140:143], v[212:215], v[44:47]
	v_mfma_f32_16x16x32_bf16 v[32:35], v[84:87], v[220:223], v[32:35]
	v_mfma_f32_16x16x32_bf16 v[28:31], v[140:143], v[220:223], v[28:31]
	v_mfma_f32_16x16x32_bf16 v[16:19], v[84:87], v[228:231], v[16:19]
	v_mfma_f32_16x16x32_bf16 v[12:15], v[140:143], v[228:231], v[12:15]
	v_mfma_f32_16x16x32_bf16 v[64:67], v[96:99], v[208:211], v[64:67]
	v_mfma_f32_16x16x32_bf16 v[60:63], v[144:147], v[208:211], v[60:63]
	v_mfma_f32_16x16x32_bf16 v[48:51], v[96:99], v[216:219], v[48:51]
	v_mfma_f32_16x16x32_bf16 v[44:47], v[144:147], v[216:219], v[44:47]
	v_mfma_f32_16x16x32_bf16 v[32:35], v[96:99], v[224:227], v[32:35]
	v_mfma_f32_16x16x32_bf16 v[28:31], v[144:147], v[224:227], v[28:31]
	v_mfma_f32_16x16x32_bf16 v[16:19], v[96:99], v[232:235], v[16:19]
	v_mfma_f32_16x16x32_bf16 v[12:15], v[144:147], v[232:235], v[12:15]
	s_setprio 0
	s_setprio 3
	v_mfma_f32_16x16x32_bf16 v[56:59], v[152:155], v[186:189], v[56:59]
	v_mfma_f32_16x16x32_bf16 v[52:55], v[160:163], v[186:189], v[52:55]
	v_mfma_f32_16x16x32_bf16 v[40:43], v[152:155], v[212:215], v[40:43]
	v_mfma_f32_16x16x32_bf16 v[36:39], v[160:163], v[212:215], v[36:39]
	v_mfma_f32_16x16x32_bf16 v[24:27], v[152:155], v[220:223], v[24:27]
	v_mfma_f32_16x16x32_bf16 v[20:23], v[160:163], v[220:223], v[20:23]
	v_mfma_f32_16x16x32_bf16 v[6:9], v[152:155], v[228:231], v[8:11]
	v_mfma_f32_16x16x32_bf16 v[2:5], v[160:163], v[228:231], v[2:5]
	v_mfma_f32_16x16x32_bf16 v[56:59], v[156:159], v[208:211], v[56:59]
	v_mfma_f32_16x16x32_bf16 v[52:55], v[182:185], v[208:211], v[52:55]
	v_mfma_f32_16x16x32_bf16 v[40:43], v[156:159], v[216:219], v[40:43]
	v_mfma_f32_16x16x32_bf16 v[36:39], v[182:185], v[216:219], v[36:39]
	v_mfma_f32_16x16x32_bf16 v[24:27], v[156:159], v[224:227], v[24:27]
	v_mfma_f32_16x16x32_bf16 v[20:23], v[182:185], v[224:227], v[20:23]
	v_mfma_f32_16x16x32_bf16 v[8:11], v[156:159], v[232:235], v[6:9]
	v_mfma_f32_16x16x32_bf16 v[4:7], v[182:185], v[232:235], v[2:5]
	s_setprio 0
	s_barrier
	s_add_i32 s95, s95, 2
	s_add_u32 s66, s66, 0x100
	s_addc_u32 s67, s67, 0
	s_cmp_gt_u32 s95, 61
	s_cbranch_scc1 .LBB0_237

; #define PG8_STAGE(bufoff, gbase, voff) do { _Pragma("unroll") for (int _i = 0; _i < 2; ++_i) \
;         __builtin_amdgcn_global_load_lds((const unsigned*)((const char*)(gbase) + (voff)[_i]), (LAS unsigned*)(lds + (bufoff) + ldsw + _i * 8192), 16, 0, 0); } while (0)
; #define PG8_LDA(dst, b, h) do { _Pragma("unroll") for (int m = 0; m < 4; ++m) _Pragma("unroll") for (int k = 0; k < 2; ++k) dst[m][k] = *(const LAS bf16x8*)(lds + PG8_SA(b, h) + aoff + m * 2048 + k * 1024); } while (0)
; #define PG8_LDB(dst, b, h) do { _Pragma("unroll") for (int n = 0; n < 2; ++n) _Pragma("unroll") for (int k = 0; k < 2; ++k) dst[n][k] = *(const LAS bf16x8*)(lds + PG8_SB(b, h) + boff + n * 2048 + k * 1024); } while (0)
; #define PG8_MMA(ai, bj, At, Bt) do { __builtin_amdgcn_s_setprio(3); _Pragma("unroll") for (int m = 0; m < 4; ++m) _Pragma("unroll") for (int n = 0; n < 2; ++n) _Pragma("unroll") for (int k = 0; k < 2; ++k) \
;         acc[ai][bj][m][n] = __builtin_amdgcn_mfma_f32_16x16x32_bf16(Bt[n][k], At[m][k], acc[ai][bj][m][n], 0, 0, 0); __builtin_amdgcn_s_setprio(0); } while (0)
; #define PG8_WAIT_V(n) asm volatile("s_waitcnt vmcnt(" #n ")" ::: "memory")
; #define PG8_WAIT_L(n) asm volatile("s_waitcnt lgkmcnt(" #n ")" ::: "memory")
; #define PG8_BAR __builtin_amdgcn_s_barrier()
; #define PG8_SCHED __builtin_amdgcn_sched_barrier(0)
; template <class Epi, class Sched, bool ALIGN_EPI = false, bool SP2 = false>
; __device__ __forceinline__ void gemm_phase(LAS unsigned char* lds, const Gemm g, const Sched& S, const Epi& E) {
;     ...
;             PG8_LDB(B0, 0, 0); PG8_LDB(B1, 0, 1); PG8_SCHED; PG8_LDA(At, 0, 0); PG8_STAGE(PG8_SA(1, 1), a1 + hsA, voffA);
;             PG8_WAIT_V(8); PG8_WAIT_L(0); PG8_BAR; PG8_MMA(0, 0, At, B0); PG8_MMA(0, 1, At, B1); PG8_BAR; PG8_SCHED;
;             PG8_LDA(At, 0, 1); PG8_STAGE(PG8_SB(0, 0), b2, voffB); PG8_STAGE(PG8_SB(0, 1), b2 + hsB, voffB); PG8_STAGE(PG8_SA(0, 0), a2, voffA);
;             PG8_WAIT_V(8); PG8_WAIT_L(0); PG8_BAR; PG8_MMA(1, 0, At, B0); PG8_MMA(1, 1, At, B1); PG8_BAR; PG8_SCHED;
.LBB0_309:
	ds_read_b128 v[112:115], v175
	ds_read_b128 v[132:135], v251
	ds_read_b128 v[136:139], v175 offset:2048
	ds_read_b128 v[140:143], v251 offset:2048
	ds_read_b128 v[144:147], v176
	ds_read_b128 v[148:151], v252
	ds_read_b128 v[184:187], v176 offset:2048
	ds_read_b128 v[188:191], v252 offset:2048
	s_add_u32 s24, s4, 0xffefc080
	s_addc_u32 s25, s5, -1
	s_cmp_eq_u32 s73, 60
	s_cselect_b32 s27, s11, s25
	s_cselect_b32 s26, s10, s24
	s_cselect_b32 s25, s21, s72
	s_cselect_b32 s24, s20, s71
	s_sub_u32 s100, s4, 0x104000
	s_subb_u32 s101, s5, 0
	v_lshl_add_u64 v[242:243], s[100:101], 0, v[152:153]
	s_mov_b32 m0, s42
	v_lshl_add_u64 v[244:245], s[100:101], 0, v[156:157]
	global_load_lds_dwordx4 v[242:243], off
	s_mov_b32 m0, s43
	s_nop 0
	global_load_lds_dwordx4 v[244:245], off
	v_lshl_add_u64 v[200:201], s[4:5], 0, v[164:165]
	s_add_i32 m0, s36, 0xc000
	ds_read_b128 v[192:195], v177
	ds_read_b128 v[196:199], v250
	ds_read_b128 v[206:209], v177 offset:2048
	ds_read_b128 v[210:213], v250 offset:2048
	ds_read_b128 v[214:217], v177 offset:4096
	ds_read_b128 v[218:221], v250 offset:4096
	ds_read_b128 v[222:225], v177 offset:6144
	ds_read_b128 v[226:229], v250 offset:6144
	global_load_lds_dwordx4 v[200:201], off
	v_lshl_add_u64 v[200:201], s[4:5], 0, v[166:167]
	s_add_i32 m0, s36, 0xe000
	s_nop 0
	global_load_lds_dwordx4 v[200:201], off
	s_waitcnt vmcnt(8)
	s_waitcnt lgkmcnt(0)
	s_barrier
	s_setprio 3
	s_waitcnt lgkmcnt(0)
	v_mfma_f32_16x16x32_bf16 v[128:131], v[112:115], v[192:195], v[128:131]
	v_mfma_f32_16x16x32_bf16 v[124:127], v[136:139], v[192:195], v[124:127]
	v_mfma_f32_16x16x32_bf16 v[108:111], v[112:115], v[206:209], v[108:111]
	v_mfma_f32_16x16x32_bf16 v[104:107], v[136:139], v[206:209], v[104:107]
	v_mfma_f32_16x16x32_bf16 v[92:95], v[112:115], v[214:217], v[92:95]
	v_mfma_f32_16x16x32_bf16 v[88:91], v[136:139], v[214:217], v[88:91]
	v_mfma_f32_16x16x32_bf16 v[76:79], v[112:115], v[222:225], v[76:79]
	v_mfma_f32_16x16x32_bf16 v[72:75], v[136:139], v[222:225], v[72:75]
	v_mfma_f32_16x16x32_bf16 v[128:131], v[132:135], v[196:199], v[128:131]
	v_mfma_f32_16x16x32_bf16 v[124:127], v[140:143], v[196:199], v[124:127]
	v_mfma_f32_16x16x32_bf16 v[108:111], v[132:135], v[210:213], v[108:111]
	v_mfma_f32_16x16x32_bf16 v[104:107], v[140:143], v[210:213], v[104:107]
	v_mfma_f32_16x16x32_bf16 v[92:95], v[132:135], v[218:221], v[92:95]
	v_mfma_f32_16x16x32_bf16 v[88:91], v[140:143], v[218:221], v[88:91]
	v_mfma_f32_16x16x32_bf16 v[76:79], v[132:135], v[226:229], v[76:79]
	v_mfma_f32_16x16x32_bf16 v[72:75], v[140:143], v[226:229], v[72:75]
	s_setprio 0
	s_setprio 3
	v_mfma_f32_16x16x32_bf16 v[120:123], v[144:147], v[192:195], v[120:123]
	v_mfma_f32_16x16x32_bf16 v[116:119], v[184:187], v[192:195], v[116:119]
	v_mfma_f32_16x16x32_bf16 v[100:103], v[144:147], v[206:209], v[100:103]
	v_mfma_f32_16x16x32_bf16 v[96:99], v[184:187], v[206:209], v[96:99]
	v_mfma_f32_16x16x32_bf16 v[84:87], v[144:147], v[214:217], v[84:87]
	v_mfma_f32_16x16x32_bf16 v[80:83], v[184:187], v[214:217], v[80:83]
	v_mfma_f32_16x16x32_bf16 v[68:71], v[144:147], v[222:225], v[68:71]
	v_mfma_f32_16x16x32_bf16 v[64:67], v[184:187], v[222:225], v[64:67]
	v_mfma_f32_16x16x32_bf16 v[120:123], v[148:151], v[196:199], v[120:123]
	v_mfma_f32_16x16x32_bf16 v[116:119], v[188:191], v[196:199], v[116:119]
	v_mfma_f32_16x16x32_bf16 v[100:103], v[148:151], v[210:213], v[100:103]
	v_mfma_f32_16x16x32_bf16 v[96:99], v[188:191], v[210:213], v[96:99]
	v_mfma_f32_16x16x32_bf16 v[84:87], v[148:151], v[218:221], v[84:87]
	v_mfma_f32_16x16x32_bf16 v[80:83], v[188:191], v[218:221], v[80:83]
	v_mfma_f32_16x16x32_bf16 v[68:71], v[148:151], v[226:229], v[68:71]
	v_mfma_f32_16x16x32_bf16 v[64:67], v[188:191], v[226:229], v[64:67]
	s_setprio 0
	s_barrier
	s_add_i32 s74, s45, s31
	v_lshl_add_u64 v[200:201], s[24:25], 0, v[154:155]
	s_mov_b32 m0, s74
	ds_read_b128 v[192:195], v177 offset:16384
	ds_read_b128 v[196:199], v250 offset:16384
	ds_read_b128 v[206:209], v177 offset:18432
	ds_read_b128 v[210:213], v250 offset:18432
	ds_read_b128 v[214:217], v177 offset:20480
	ds_read_b128 v[218:221], v250 offset:20480
	ds_read_b128 v[222:225], v177 offset:22528
	ds_read_b128 v[226:229], v250 offset:22528
	global_load_lds_dwordx4 v[200:201], off
	s_add_i32 m0, s74, 0x2000
	s_add_u32 s74, s24, 0x41000
	v_lshl_add_u64 v[230:231], s[24:25], 0, v[158:159]
	s_addc_u32 s75, s25, 0
	s_add_i32 s78, s46, s31
	global_load_lds_dwordx4 v[230:231], off
	v_lshl_add_u64 v[232:233], s[74:75], 0, v[154:155]
	s_mov_b32 m0, s78
	s_nop 0
	global_load_lds_dwordx4 v[232:233], off
	v_lshl_add_u64 v[232:233], s[74:75], 0, v[158:159]
	s_add_i32 m0, s78, 0x2000
	s_nop 0
	global_load_lds_dwordx4 v[232:233], off
	s_waitcnt vmcnt(6)
	s_waitcnt lgkmcnt(0)
	s_barrier
; #define PG8_STAGE(bufoff, gbase, voff) do { _Pragma("unroll") for (int _i = 0; _i < 2; ++_i) \
;         __builtin_amdgcn_global_load_lds((const unsigned*)((const char*)(gbase) + (voff)[_i]), (LAS unsigned*)(lds + (bufoff) + ldsw + _i * 8192), 16, 0, 0); } while (0)
; #define PG8_LDA(dst, b, h) do { _Pragma("unroll") for (int m = 0; m < 4; ++m) _Pragma("unroll") for (int k = 0; k < 2; ++k) dst[m][k] = *(const LAS bf16x8*)(lds + PG8_SA(b, h) + aoff + m * 2048 + k * 1024); } while (0)
; #define PG8_LDB(dst, b, h) do { _Pragma("unroll") for (int n = 0; n < 2; ++n) _Pragma("unroll") for (int k = 0; k < 2; ++k) dst[n][k] = *(const LAS bf16x8*)(lds + PG8_SB(b, h) + boff + n * 2048 + k * 1024); } while (0)
; #define PG8_MMA(ai, bj, At, Bt) do { __builtin_amdgcn_s_setprio(3); _Pragma("unroll") for (int m = 0; m < 4; ++m) _Pragma("unroll") for (int n = 0; n < 2; ++n) _Pragma("unroll") for (int k = 0; k < 2; ++k) \
;         acc[ai][bj][m][n] = __builtin_amdgcn_mfma_f32_16x16x32_bf16(Bt[n][k], At[m][k], acc[ai][bj][m][n], 0, 0, 0); __builtin_amdgcn_s_setprio(0); } while (0)
; #define PG8_WAIT_V(n) asm volatile("s_waitcnt vmcnt(" #n ")" ::: "memory")
; #define PG8_WAIT_L(n) asm volatile("s_waitcnt lgkmcnt(" #n ")" ::: "memory")
; #define PG8_BAR __builtin_amdgcn_s_barrier()
; #define PG8_SCHED __builtin_amdgcn_sched_barrier(0)
; template <class Epi, class Sched, bool ALIGN_EPI = false, bool SP2 = false>
; __device__ __forceinline__ void gemm_phase(LAS unsigned char* lds, const Gemm g, const Sched& S, const Epi& E) {
;     ...
;             PG8_WAIT_V(8); PG8_WAIT_L(0); PG8_BAR; PG8_MMA(1, 0, At, B0); PG8_MMA(1, 1, At, B1); PG8_BAR; PG8_SCHED;
;             PG8_LDB(B0, 1, 0); PG8_LDB(B1, 1, 1); PG8_SCHED; PG8_LDA(At, 1, 0); PG8_STAGE(PG8_SA(0, 1), a2 + hsA, voffA);
;             PG8_WAIT_V(8); PG8_WAIT_L(0); PG8_BAR; PG8_MMA(0, 0, At, B0); PG8_MMA(0, 1, At, B1); PG8_BAR; PG8_SCHED;
	s_setprio 3
	s_waitcnt lgkmcnt(0)
	v_mfma_f32_16x16x32_bf16 v[60:63], v[112:115], v[192:195], v[60:63]
	v_mfma_f32_16x16x32_bf16 v[56:59], v[136:139], v[192:195], v[56:59]
	v_mfma_f32_16x16x32_bf16 v[44:47], v[112:115], v[206:209], v[44:47]
	v_mfma_f32_16x16x32_bf16 v[40:43], v[136:139], v[206:209], v[40:43]
	v_mfma_f32_16x16x32_bf16 v[28:31], v[112:115], v[214:217], v[28:31]
	v_mfma_f32_16x16x32_bf16 v[24:27], v[136:139], v[214:217], v[24:27]
	v_mfma_f32_16x16x32_bf16 v[12:15], v[112:115], v[222:225], v[12:15]
	v_mfma_f32_16x16x32_bf16 v[8:11], v[136:139], v[222:225], v[8:11]
	v_mfma_f32_16x16x32_bf16 v[60:63], v[132:135], v[196:199], v[60:63]
	v_mfma_f32_16x16x32_bf16 v[56:59], v[140:143], v[196:199], v[56:59]
	v_mfma_f32_16x16x32_bf16 v[44:47], v[132:135], v[210:213], v[44:47]
	v_mfma_f32_16x16x32_bf16 v[40:43], v[140:143], v[210:213], v[40:43]
	v_mfma_f32_16x16x32_bf16 v[28:31], v[132:135], v[218:221], v[28:31]
	v_mfma_f32_16x16x32_bf16 v[24:27], v[140:143], v[218:221], v[24:27]
	v_mfma_f32_16x16x32_bf16 v[12:15], v[132:135], v[226:229], v[12:15]
	v_mfma_f32_16x16x32_bf16 v[8:11], v[140:143], v[226:229], v[8:11]
	s_setprio 0
	s_setprio 3
	v_mfma_f32_16x16x32_bf16 v[52:55], v[144:147], v[192:195], v[52:55]
	v_mfma_f32_16x16x32_bf16 v[48:51], v[184:187], v[192:195], v[48:51]
	v_mfma_f32_16x16x32_bf16 v[36:39], v[144:147], v[206:209], v[36:39]
	v_mfma_f32_16x16x32_bf16 v[32:35], v[184:187], v[206:209], v[32:35]
	v_mfma_f32_16x16x32_bf16 v[20:23], v[144:147], v[214:217], v[20:23]
	v_mfma_f32_16x16x32_bf16 v[16:19], v[184:187], v[214:217], v[16:19]
	v_mfma_f32_16x16x32_bf16 v[4:7], v[144:147], v[222:225], v[4:7]
	v_mfma_f32_16x16x32_bf16 v[0:3], v[184:187], v[222:225], v[0:3]
	v_mfma_f32_16x16x32_bf16 v[52:55], v[148:151], v[196:199], v[52:55]
	v_mfma_f32_16x16x32_bf16 v[48:51], v[188:191], v[196:199], v[48:51]
	v_mfma_f32_16x16x32_bf16 v[36:39], v[148:151], v[210:213], v[36:39]
	v_mfma_f32_16x16x32_bf16 v[32:35], v[188:191], v[210:213], v[32:35]
	v_mfma_f32_16x16x32_bf16 v[20:23], v[148:151], v[218:221], v[20:23]
	v_mfma_f32_16x16x32_bf16 v[16:19], v[188:191], v[218:221], v[16:19]
	v_mfma_f32_16x16x32_bf16 v[4:7], v[148:151], v[226:229], v[4:7]
	v_mfma_f32_16x16x32_bf16 v[0:3], v[188:191], v[226:229], v[0:3]
	s_setprio 0
	s_barrier
	s_add_i32 s74, 0, 0x18000
	s_add_i32 s75, 0, 0x1c000
	v_add_u32_e32 v140, s74, v173
	v_xor_b32_e32 v253, 64, v140
	v_add_u32_e32 v188, s75, v173
	v_xor_b32_e32 v254, 64, v188
	ds_read_b128 v[112:115], v140
	ds_read_b128 v[132:135], v253
	ds_read_b128 v[136:139], v140 offset:2048
	ds_read_b128 v[140:143], v253 offset:2048
	ds_read_b128 v[144:147], v188
	ds_read_b128 v[148:151], v254
	ds_read_b128 v[184:187], v188 offset:2048
	ds_read_b128 v[188:191], v254 offset:2048
	v_lshl_add_u64 v[242:243], s[26:27], 0, v[152:153]
	s_mov_b32 m0, s36
	v_lshl_add_u64 v[244:245], s[26:27], 0, v[156:157]
	global_load_lds_dwordx4 v[242:243], off
	s_mov_b32 m0, s37
	s_nop 0
	global_load_lds_dwordx4 v[244:245], off
	s_add_u32 s26, s26, 0x104000
	s_addc_u32 s27, s27, 0
	s_mov_b32 m0, s38
	v_lshl_add_u64 v[236:237], s[26:27], 0, v[152:153]
	ds_read_b128 v[192:195], v177 offset:32768
	ds_read_b128 v[196:199], v250 offset:32768
	ds_read_b128 v[206:209], v177 offset:34816
	ds_read_b128 v[210:213], v250 offset:34816
	ds_read_b128 v[214:217], v177 offset:36864
	ds_read_b128 v[218:221], v250 offset:36864
	ds_read_b128 v[222:225], v177 offset:38912
	ds_read_b128 v[226:229], v250 offset:38912
	global_load_lds_dwordx4 v[236:237], off
	v_lshl_add_u64 v[236:237], s[26:27], 0, v[156:157]
	s_mov_b32 m0, s39
	s_nop 0
	global_load_lds_dwordx4 v[236:237], off
	s_waitcnt vmcnt(8)
	s_waitcnt lgkmcnt(0)
	s_barrier
; #define PG8_STAGE(bufoff, gbase, voff) do { _Pragma("unroll") for (int _i = 0; _i < 2; ++_i) \
;         __builtin_amdgcn_global_load_lds((const unsigned*)((const char*)(gbase) + (voff)[_i]), (LAS unsigned*)(lds + (bufoff) + ldsw + _i * 8192), 16, 0, 0); } while (0)
; #define PG8_LDA(dst, b, h) do { _Pragma("unroll") for (int m = 0; m < 4; ++m) _Pragma("unroll") for (int k = 0; k < 2; ++k) dst[m][k] = *(const LAS bf16x8*)(lds + PG8_SA(b, h) + aoff + m * 2048 + k * 1024); } while (0)
; #define PG8_MMA(ai, bj, At, Bt) do { __builtin_amdgcn_s_setprio(3); _Pragma("unroll") for (int m = 0; m < 4; ++m) _Pragma("unroll") for (int n = 0; n < 2; ++n) _Pragma("unroll") for (int k = 0; k < 2; ++k) \
;         acc[ai][bj][m][n] = __builtin_amdgcn_mfma_f32_16x16x32_bf16(Bt[n][k], At[m][k], acc[ai][bj][m][n], 0, 0, 0); __builtin_amdgcn_s_setprio(0); } while (0)
; #define PG8_WAIT_V(n) asm volatile("s_waitcnt vmcnt(" #n ")" ::: "memory")
; #define PG8_WAIT_L(n) asm volatile("s_waitcnt lgkmcnt(" #n ")" ::: "memory")
; #define PG8_BAR __builtin_amdgcn_s_barrier()
; #define PG8_SCHED __builtin_amdgcn_sched_barrier(0)
; template <class Epi, class Sched, bool ALIGN_EPI = false, bool SP2 = false>
; __device__ __forceinline__ void gemm_phase(LAS unsigned char* lds, const Gemm g, const Sched& S, const Epi& E) {
;     ...
;             PG8_WAIT_V(8); PG8_WAIT_L(0); PG8_BAR; PG8_MMA(0, 0, At, B0); PG8_MMA(0, 1, At, B1); PG8_BAR; PG8_SCHED;
;             PG8_LDA(At, 1, 1); PG8_STAGE(PG8_SB(1, 0), b3, voffB); PG8_STAGE(PG8_SB(1, 1), b3 + hsB, voffB); PG8_STAGE(PG8_SA(1, 0), a3, voffA);
;             PG8_WAIT_V(8); PG8_WAIT_L(0); PG8_BAR; PG8_MMA(1, 0, At, B0); PG8_MMA(1, 1, At, B1); PG8_BAR; PG8_SCHED;
	s_setprio 3
	s_waitcnt lgkmcnt(0)
	v_mfma_f32_16x16x32_bf16 v[128:131], v[112:115], v[192:195], v[128:131]
	v_mfma_f32_16x16x32_bf16 v[124:127], v[136:139], v[192:195], v[124:127]
	v_mfma_f32_16x16x32_bf16 v[108:111], v[112:115], v[206:209], v[108:111]
	v_mfma_f32_16x16x32_bf16 v[104:107], v[136:139], v[206:209], v[104:107]
	v_mfma_f32_16x16x32_bf16 v[92:95], v[112:115], v[214:217], v[92:95]
	v_mfma_f32_16x16x32_bf16 v[88:91], v[136:139], v[214:217], v[88:91]
	v_mfma_f32_16x16x32_bf16 v[76:79], v[112:115], v[222:225], v[76:79]
	v_mfma_f32_16x16x32_bf16 v[72:75], v[136:139], v[222:225], v[72:75]
	v_mfma_f32_16x16x32_bf16 v[128:131], v[132:135], v[196:199], v[128:131]
	v_mfma_f32_16x16x32_bf16 v[124:127], v[140:143], v[196:199], v[124:127]
	v_mfma_f32_16x16x32_bf16 v[108:111], v[132:135], v[210:213], v[108:111]
	v_mfma_f32_16x16x32_bf16 v[104:107], v[140:143], v[210:213], v[104:107]
	v_mfma_f32_16x16x32_bf16 v[92:95], v[132:135], v[218:221], v[92:95]
	v_mfma_f32_16x16x32_bf16 v[88:91], v[140:143], v[218:221], v[88:91]
	v_mfma_f32_16x16x32_bf16 v[76:79], v[132:135], v[226:229], v[76:79]
	v_mfma_f32_16x16x32_bf16 v[72:75], v[140:143], v[226:229], v[72:75]
	s_setprio 0
	s_setprio 3
	v_mfma_f32_16x16x32_bf16 v[120:123], v[144:147], v[192:195], v[120:123]
	v_mfma_f32_16x16x32_bf16 v[116:119], v[184:187], v[192:195], v[116:119]
	v_mfma_f32_16x16x32_bf16 v[100:103], v[144:147], v[206:209], v[100:103]
	v_mfma_f32_16x16x32_bf16 v[96:99], v[184:187], v[206:209], v[96:99]
	v_mfma_f32_16x16x32_bf16 v[84:87], v[144:147], v[214:217], v[84:87]
	v_mfma_f32_16x16x32_bf16 v[80:83], v[184:187], v[214:217], v[80:83]
	v_mfma_f32_16x16x32_bf16 v[68:71], v[144:147], v[222:225], v[68:71]
	v_mfma_f32_16x16x32_bf16 v[64:67], v[184:187], v[222:225], v[64:67]
	v_mfma_f32_16x16x32_bf16 v[120:123], v[148:151], v[196:199], v[120:123]
	v_mfma_f32_16x16x32_bf16 v[116:119], v[188:191], v[196:199], v[116:119]
	v_mfma_f32_16x16x32_bf16 v[100:103], v[148:151], v[210:213], v[100:103]
	v_mfma_f32_16x16x32_bf16 v[96:99], v[188:191], v[210:213], v[96:99]
	v_mfma_f32_16x16x32_bf16 v[84:87], v[148:151], v[218:221], v[84:87]
	v_mfma_f32_16x16x32_bf16 v[80:83], v[188:191], v[218:221], v[80:83]
	v_mfma_f32_16x16x32_bf16 v[68:71], v[148:151], v[226:229], v[68:71]
	v_mfma_f32_16x16x32_bf16 v[64:67], v[188:191], v[226:229], v[64:67]
	s_setprio 0
	s_barrier
	s_add_i32 s26, s74, s31
	v_lshl_add_u64 v[200:201], v[200:201], 0, s[14:15]
	s_mov_b32 m0, s26
	ds_read_b128 v[192:195], v177 offset:49152
	ds_read_b128 v[196:199], v250 offset:49152
	ds_read_b128 v[206:209], v177 offset:51200
	ds_read_b128 v[210:213], v250 offset:51200
	ds_read_b128 v[214:217], v177 offset:53248
	ds_read_b128 v[218:221], v250 offset:53248
	ds_read_b128 v[222:225], v177 offset:55296
	ds_read_b128 v[226:229], v250 offset:55296
	global_load_lds_dwordx4 v[200:201], off
	s_add_i32 m0, s26, 0x2000
	s_add_u32 s24, s24, 0x41080
	v_lshl_add_u64 v[200:201], v[230:231], 0, s[14:15]
	s_addc_u32 s25, s25, 0
	s_add_i32 s26, s75, s31
	global_load_lds_dwordx4 v[200:201], off
	v_lshl_add_u64 v[200:201], s[24:25], 0, v[154:155]
	s_mov_b32 m0, s26
	s_nop 0
	global_load_lds_dwordx4 v[200:201], off
	v_lshl_add_u64 v[200:201], s[24:25], 0, v[158:159]
	s_add_i32 m0, s26, 0x2000
	s_nop 0
	global_load_lds_dwordx4 v[200:201], off
	s_waitcnt vmcnt(6)
	s_waitcnt lgkmcnt(0)
	s_barrier
	s_setprio 3
	s_waitcnt lgkmcnt(0)
	v_mfma_f32_16x16x32_bf16 v[60:63], v[112:115], v[192:195], v[60:63]
	v_mfma_f32_16x16x32_bf16 v[56:59], v[136:139], v[192:195], v[56:59]
	v_mfma_f32_16x16x32_bf16 v[44:47], v[112:115], v[206:209], v[44:47]
	v_mfma_f32_16x16x32_bf16 v[40:43], v[136:139], v[206:209], v[40:43]
	v_mfma_f32_16x16x32_bf16 v[28:31], v[112:115], v[214:217], v[28:31]
	v_mfma_f32_16x16x32_bf16 v[24:27], v[136:139], v[214:217], v[24:27]
	v_mfma_f32_16x16x32_bf16 v[12:15], v[112:115], v[222:225], v[12:15]
	v_mfma_f32_16x16x32_bf16 v[8:11], v[136:139], v[222:225], v[8:11]
	v_mfma_f32_16x16x32_bf16 v[60:63], v[132:135], v[196:199], v[60:63]
	v_mfma_f32_16x16x32_bf16 v[56:59], v[140:143], v[196:199], v[56:59]
	v_mfma_f32_16x16x32_bf16 v[44:47], v[132:135], v[210:213], v[44:47]
	v_mfma_f32_16x16x32_bf16 v[40:43], v[140:143], v[210:213], v[40:43]
	v_mfma_f32_16x16x32_bf16 v[28:31], v[132:135], v[218:221], v[28:31]
	v_mfma_f32_16x16x32_bf16 v[24:27], v[140:143], v[218:221], v[24:27]
	v_mfma_f32_16x16x32_bf16 v[12:15], v[132:135], v[226:229], v[12:15]
	v_mfma_f32_16x16x32_bf16 v[8:11], v[140:143], v[226:229], v[8:11]
	s_setprio 0
	s_setprio 3
	v_mfma_f32_16x16x32_bf16 v[52:55], v[144:147], v[192:195], v[52:55]
	v_mfma_f32_16x16x32_bf16 v[48:51], v[184:187], v[192:195], v[48:51]
	v_mfma_f32_16x16x32_bf16 v[36:39], v[144:147], v[206:209], v[36:39]
	v_mfma_f32_16x16x32_bf16 v[32:35], v[184:187], v[206:209], v[32:35]
	v_mfma_f32_16x16x32_bf16 v[20:23], v[144:147], v[214:217], v[20:23]
	v_mfma_f32_16x16x32_bf16 v[16:19], v[184:187], v[214:217], v[16:19]
	v_mfma_f32_16x16x32_bf16 v[4:7], v[144:147], v[222:225], v[4:7]
	v_mfma_f32_16x16x32_bf16 v[0:3], v[184:187], v[222:225], v[0:3]
	v_mfma_f32_16x16x32_bf16 v[52:55], v[148:151], v[196:199], v[52:55]
	v_mfma_f32_16x16x32_bf16 v[48:51], v[188:191], v[196:199], v[48:51]
	v_mfma_f32_16x16x32_bf16 v[36:39], v[148:151], v[210:213], v[36:39]
	v_mfma_f32_16x16x32_bf16 v[32:35], v[188:191], v[210:213], v[32:35]
	v_mfma_f32_16x16x32_bf16 v[20:23], v[148:151], v[218:221], v[20:23]
	v_mfma_f32_16x16x32_bf16 v[16:19], v[188:191], v[218:221], v[16:19]
	v_mfma_f32_16x16x32_bf16 v[4:7], v[148:151], v[226:229], v[4:7]
	v_mfma_f32_16x16x32_bf16 v[0:3], v[188:191], v[226:229], v[0:3]
	s_setprio 0
	s_barrier
	s_add_i32 s73, s73, 2
	s_add_u32 s4, s4, 0x100
	s_addc_u32 s5, s5, 0
	s_add_u32 s71, s71, 0x100
	s_addc_u32 s72, s72, 0
	s_cmp_gt_u32 s73, 61
	s_cbranch_scc0 .LBB0_309
	s_and_b64 vcc, exec, s[16:17]
	s_cbranch_vccz .LBB0_312
	s_barrier

; #define PG8_STAGE(bufoff, gbase, voff) do { _Pragma("unroll") for (int _i = 0; _i < 2; ++_i) \
;         __builtin_amdgcn_global_load_lds((const unsigned*)((const char*)(gbase) + (voff)[_i]), (LAS unsigned*)(lds + (bufoff) + ldsw + _i * 8192), 16, 0, 0); } while (0)
; #define PG8_LDA(dst, b, h) do { _Pragma("unroll") for (int m = 0; m < 4; ++m) _Pragma("unroll") for (int k = 0; k < 2; ++k) dst[m][k] = *(const LAS bf16x8*)(lds + PG8_SA(b, h) + aoff + m * 2048 + k * 1024); } while (0)
; #define PG8_LDB(dst, b, h) do { _Pragma("unroll") for (int n = 0; n < 2; ++n) _Pragma("unroll") for (int k = 0; k < 2; ++k) dst[n][k] = *(const LAS bf16x8*)(lds + PG8_SB(b, h) + boff + n * 2048 + k * 1024); } while (0)
; #define PG8_MMA(ai, bj, At, Bt) do { __builtin_amdgcn_s_setprio(3); _Pragma("unroll") for (int m = 0; m < 4; ++m) _Pragma("unroll") for (int n = 0; n < 2; ++n) _Pragma("unroll") for (int k = 0; k < 2; ++k) \
;         acc[ai][bj][m][n] = __builtin_amdgcn_mfma_f32_16x16x32_bf16(Bt[n][k], At[m][k], acc[ai][bj][m][n], 0, 0, 0); __builtin_amdgcn_s_setprio(0); } while (0)
; #define PG8_WAIT_V(n) asm volatile("s_waitcnt vmcnt(" #n ")" ::: "memory")
; #define PG8_WAIT_L(n) asm volatile("s_waitcnt lgkmcnt(" #n ")" ::: "memory")
; #define PG8_BAR __builtin_amdgcn_s_barrier()
; #define PG8_SCHED __builtin_amdgcn_sched_barrier(0)
; template <class Epi, class Sched, bool ALIGN_EPI = false, bool SP2 = false>
; __device__ __forceinline__ void gemm_phase(LAS unsigned char* lds, const Gemm g, const Sched& S, const Epi& E) {
;     ...
;             PG8_LDB(B0, 0, 0); PG8_LDB(B1, 0, 1); PG8_SCHED; PG8_LDA(At, 0, 0); PG8_STAGE(PG8_SA(1, 1), a1 + hsA, voffA);
;             PG8_WAIT_V(8); PG8_WAIT_L(0); PG8_BAR; PG8_MMA(0, 0, At, B0); PG8_MMA(0, 1, At, B1); PG8_BAR; PG8_SCHED;
;             PG8_LDA(At, 0, 1); PG8_STAGE(PG8_SB(0, 0), b2, voffB); PG8_STAGE(PG8_SB(0, 1), b2 + hsB, voffB); PG8_STAGE(PG8_SA(0, 0), a2, voffA);
;             PG8_WAIT_V(8); PG8_WAIT_L(0); PG8_BAR; PG8_MMA(1, 0, At, B0); PG8_MMA(1, 1, At, B1); PG8_BAR; PG8_SCHED;
.LBB0_350:
	ds_read_b128 v[140:143], v149
	ds_read_b128 v[156:159], v251
	ds_read_b128 v[160:163], v149 offset:2048
	ds_read_b128 v[164:167], v251 offset:2048
	ds_read_b128 v[168:171], v150
	ds_read_b128 v[172:175], v252
	ds_read_b128 v[176:179], v150 offset:2048
	ds_read_b128 v[180:183], v252 offset:2048
	s_add_u32 s16, s14, 0xffbfc080
	s_addc_u32 s17, s15, -1
	s_cmpk_eq_i32 s50, 0xfc
	s_cselect_b32 s21, s5, s17
	s_cselect_b32 s20, s4, s16
	s_cselect_b32 s17, s13, s49
	s_cselect_b32 s16, s12, s48
	s_sub_u32 s100, s14, 0x404000
	s_subb_u32 s101, s15, 0
	v_lshl_add_u64 v[242:243], s[100:101], 0, v[128:129]
	s_mov_b32 m0, s33
	v_lshl_add_u64 v[244:245], s[100:101], 0, v[130:131]
	global_load_lds_dwordx4 v[242:243], off
	s_mov_b32 m0, s38
	s_nop 0
	global_load_lds_dwordx4 v[244:245], off
	v_lshl_add_u64 v[144:145], s[14:15], 0, v[132:133]
	s_add_i32 m0, s26, 0xc000
	ds_read_b128 v[184:187], v151
	ds_read_b128 v[188:191], v250
	ds_read_b128 v[192:195], v151 offset:2048
	ds_read_b128 v[196:199], v250 offset:2048
	ds_read_b128 v[200:203], v151 offset:4096
	ds_read_b128 v[204:207], v250 offset:4096
	ds_read_b128 v[208:211], v151 offset:6144
	ds_read_b128 v[212:215], v250 offset:6144
	global_load_lds_dwordx4 v[144:145], off
	v_lshl_add_u64 v[144:145], s[14:15], 0, v[134:135]
	s_add_i32 m0, s26, 0xe000
	s_nop 0
	global_load_lds_dwordx4 v[144:145], off
	s_waitcnt vmcnt(8)
	s_waitcnt lgkmcnt(0)
	s_barrier
	s_setprio 3
	s_waitcnt lgkmcnt(0)
	v_mfma_f32_16x16x32_bf16 v[124:127], v[140:143], v[184:187], v[124:127]
	v_mfma_f32_16x16x32_bf16 v[120:123], v[160:163], v[184:187], v[120:123]
	v_mfma_f32_16x16x32_bf16 v[108:111], v[140:143], v[192:195], v[108:111]
	v_mfma_f32_16x16x32_bf16 v[104:107], v[160:163], v[192:195], v[104:107]
	v_mfma_f32_16x16x32_bf16 v[92:95], v[140:143], v[200:203], v[92:95]
	v_mfma_f32_16x16x32_bf16 v[88:91], v[160:163], v[200:203], v[88:91]
	v_mfma_f32_16x16x32_bf16 v[76:79], v[140:143], v[208:211], v[76:79]
	v_mfma_f32_16x16x32_bf16 v[72:75], v[160:163], v[208:211], v[72:75]
	v_mfma_f32_16x16x32_bf16 v[124:127], v[156:159], v[188:191], v[124:127]
	v_mfma_f32_16x16x32_bf16 v[120:123], v[164:167], v[188:191], v[120:123]
	v_mfma_f32_16x16x32_bf16 v[108:111], v[156:159], v[196:199], v[108:111]
	v_mfma_f32_16x16x32_bf16 v[104:107], v[164:167], v[196:199], v[104:107]
	v_mfma_f32_16x16x32_bf16 v[92:95], v[156:159], v[204:207], v[92:95]
	v_mfma_f32_16x16x32_bf16 v[88:91], v[164:167], v[204:207], v[88:91]
	v_mfma_f32_16x16x32_bf16 v[76:79], v[156:159], v[212:215], v[76:79]
	v_mfma_f32_16x16x32_bf16 v[72:75], v[164:167], v[212:215], v[72:75]
	s_setprio 0
	s_setprio 3
	v_mfma_f32_16x16x32_bf16 v[116:119], v[168:171], v[184:187], v[116:119]
	v_mfma_f32_16x16x32_bf16 v[112:115], v[176:179], v[184:187], v[112:115]
	v_mfma_f32_16x16x32_bf16 v[100:103], v[168:171], v[192:195], v[100:103]
	v_mfma_f32_16x16x32_bf16 v[96:99], v[176:179], v[192:195], v[96:99]
	v_mfma_f32_16x16x32_bf16 v[84:87], v[168:171], v[200:203], v[84:87]
	v_mfma_f32_16x16x32_bf16 v[80:83], v[176:179], v[200:203], v[80:83]
	v_mfma_f32_16x16x32_bf16 v[68:71], v[168:171], v[208:211], v[68:71]
	v_mfma_f32_16x16x32_bf16 v[64:67], v[176:179], v[208:211], v[64:67]
	v_mfma_f32_16x16x32_bf16 v[116:119], v[172:175], v[188:191], v[116:119]
	v_mfma_f32_16x16x32_bf16 v[112:115], v[180:183], v[188:191], v[112:115]
	v_mfma_f32_16x16x32_bf16 v[100:103], v[172:175], v[196:199], v[100:103]
	v_mfma_f32_16x16x32_bf16 v[96:99], v[180:183], v[196:199], v[96:99]
	v_mfma_f32_16x16x32_bf16 v[84:87], v[172:175], v[204:207], v[84:87]
	v_mfma_f32_16x16x32_bf16 v[80:83], v[180:183], v[204:207], v[80:83]
	v_mfma_f32_16x16x32_bf16 v[68:71], v[172:175], v[212:215], v[68:71]
	v_mfma_f32_16x16x32_bf16 v[64:67], v[180:183], v[212:215], v[64:67]
	s_setprio 0
	s_barrier
	s_add_i32 s51, s41, s25
	v_lshl_add_u64 v[144:145], s[16:17], 0, v[128:129]
	s_mov_b32 m0, s51
	ds_read_b128 v[184:187], v151 offset:16384
	ds_read_b128 v[188:191], v250 offset:16384
	ds_read_b128 v[192:195], v151 offset:18432
	ds_read_b128 v[196:199], v250 offset:18432
	ds_read_b128 v[200:203], v151 offset:20480
	ds_read_b128 v[204:207], v250 offset:20480
	ds_read_b128 v[208:211], v151 offset:22528
	ds_read_b128 v[212:215], v250 offset:22528
	global_load_lds_dwordx4 v[144:145], off
	s_add_i32 m0, s51, 0x2000
	s_add_u32 s52, s16, 0x404000
	v_lshl_add_u64 v[216:217], s[16:17], 0, v[130:131]
	s_addc_u32 s53, s17, 0
	s_add_i32 s51, s42, s25
	global_load_lds_dwordx4 v[216:217], off
	v_lshl_add_u64 v[218:219], s[52:53], 0, v[128:129]
	s_mov_b32 m0, s51
	s_nop 0
	global_load_lds_dwordx4 v[218:219], off
	v_lshl_add_u64 v[218:219], s[52:53], 0, v[130:131]
	s_add_i32 m0, s51, 0x2000
	s_nop 0
	global_load_lds_dwordx4 v[218:219], off
	s_waitcnt vmcnt(6)
	s_waitcnt lgkmcnt(0)
	s_barrier
; #define PG8_STAGE(bufoff, gbase, voff) do { _Pragma("unroll") for (int _i = 0; _i < 2; ++_i) \
;         __builtin_amdgcn_global_load_lds((const unsigned*)((const char*)(gbase) + (voff)[_i]), (LAS unsigned*)(lds + (bufoff) + ldsw + _i * 8192), 16, 0, 0); } while (0)
; #define PG8_LDA(dst, b, h) do { _Pragma("unroll") for (int m = 0; m < 4; ++m) _Pragma("unroll") for (int k = 0; k < 2; ++k) dst[m][k] = *(const LAS bf16x8*)(lds + PG8_SA(b, h) + aoff + m * 2048 + k * 1024); } while (0)
; #define PG8_LDB(dst, b, h) do { _Pragma("unroll") for (int n = 0; n < 2; ++n) _Pragma("unroll") for (int k = 0; k < 2; ++k) dst[n][k] = *(const LAS bf16x8*)(lds + PG8_SB(b, h) + boff + n * 2048 + k * 1024); } while (0)
; #define PG8_MMA(ai, bj, At, Bt) do { __builtin_amdgcn_s_setprio(3); _Pragma("unroll") for (int m = 0; m < 4; ++m) _Pragma("unroll") for (int n = 0; n < 2; ++n) _Pragma("unroll") for (int k = 0; k < 2; ++k) \
;         acc[ai][bj][m][n] = __builtin_amdgcn_mfma_f32_16x16x32_bf16(Bt[n][k], At[m][k], acc[ai][bj][m][n], 0, 0, 0); __builtin_amdgcn_s_setprio(0); } while (0)
; #define PG8_WAIT_V(n) asm volatile("s_waitcnt vmcnt(" #n ")" ::: "memory")
; #define PG8_WAIT_L(n) asm volatile("s_waitcnt lgkmcnt(" #n ")" ::: "memory")
; #define PG8_BAR __builtin_amdgcn_s_barrier()
; #define PG8_SCHED __builtin_amdgcn_sched_barrier(0)
; template <class Epi, class Sched, bool ALIGN_EPI = false, bool SP2 = false>
; __device__ __forceinline__ void gemm_phase(LAS unsigned char* lds, const Gemm g, const Sched& S, const Epi& E) {
;     ...
;             PG8_WAIT_V(8); PG8_WAIT_L(0); PG8_BAR; PG8_MMA(1, 0, At, B0); PG8_MMA(1, 1, At, B1); PG8_BAR; PG8_SCHED;
;             PG8_LDB(B0, 1, 0); PG8_LDB(B1, 1, 1); PG8_SCHED; PG8_LDA(At, 1, 0); PG8_STAGE(PG8_SA(0, 1), a2 + hsA, voffA);
;             PG8_WAIT_V(8); PG8_WAIT_L(0); PG8_BAR; PG8_MMA(0, 0, At, B0); PG8_MMA(0, 1, At, B1); PG8_BAR; PG8_SCHED;
	s_setprio 3
	s_waitcnt lgkmcnt(0)
	v_mfma_f32_16x16x32_bf16 v[60:63], v[140:143], v[184:187], v[60:63]
	v_mfma_f32_16x16x32_bf16 v[56:59], v[160:163], v[184:187], v[56:59]
	v_mfma_f32_16x16x32_bf16 v[44:47], v[140:143], v[192:195], v[44:47]
	v_mfma_f32_16x16x32_bf16 v[40:43], v[160:163], v[192:195], v[40:43]
	v_mfma_f32_16x16x32_bf16 v[28:31], v[140:143], v[200:203], v[28:31]
	v_mfma_f32_16x16x32_bf16 v[24:27], v[160:163], v[200:203], v[24:27]
	v_mfma_f32_16x16x32_bf16 v[12:15], v[140:143], v[208:211], v[12:15]
	v_mfma_f32_16x16x32_bf16 v[8:11], v[160:163], v[208:211], v[8:11]
	v_mfma_f32_16x16x32_bf16 v[60:63], v[156:159], v[188:191], v[60:63]
	v_mfma_f32_16x16x32_bf16 v[56:59], v[164:167], v[188:191], v[56:59]
	v_mfma_f32_16x16x32_bf16 v[44:47], v[156:159], v[196:199], v[44:47]
	v_mfma_f32_16x16x32_bf16 v[40:43], v[164:167], v[196:199], v[40:43]
	v_mfma_f32_16x16x32_bf16 v[28:31], v[156:159], v[204:207], v[28:31]
	v_mfma_f32_16x16x32_bf16 v[24:27], v[164:167], v[204:207], v[24:27]
	v_mfma_f32_16x16x32_bf16 v[12:15], v[156:159], v[212:215], v[12:15]
	v_mfma_f32_16x16x32_bf16 v[8:11], v[164:167], v[212:215], v[8:11]
	s_setprio 0
	s_setprio 3
	v_mfma_f32_16x16x32_bf16 v[52:55], v[168:171], v[184:187], v[52:55]
	v_mfma_f32_16x16x32_bf16 v[48:51], v[176:179], v[184:187], v[48:51]
	v_mfma_f32_16x16x32_bf16 v[36:39], v[168:171], v[192:195], v[36:39]
	v_mfma_f32_16x16x32_bf16 v[32:35], v[176:179], v[192:195], v[32:35]
	v_mfma_f32_16x16x32_bf16 v[20:23], v[168:171], v[200:203], v[20:23]
	v_mfma_f32_16x16x32_bf16 v[16:19], v[176:179], v[200:203], v[16:19]
	v_mfma_f32_16x16x32_bf16 v[4:7], v[168:171], v[208:211], v[4:7]
	v_mfma_f32_16x16x32_bf16 v[0:3], v[176:179], v[208:211], v[0:3]
	v_mfma_f32_16x16x32_bf16 v[52:55], v[172:175], v[188:191], v[52:55]
	v_mfma_f32_16x16x32_bf16 v[48:51], v[180:183], v[188:191], v[48:51]
	v_mfma_f32_16x16x32_bf16 v[36:39], v[172:175], v[196:199], v[36:39]
	v_mfma_f32_16x16x32_bf16 v[32:35], v[180:183], v[196:199], v[32:35]
	v_mfma_f32_16x16x32_bf16 v[20:23], v[172:175], v[204:207], v[20:23]
	v_mfma_f32_16x16x32_bf16 v[16:19], v[180:183], v[204:207], v[16:19]
	v_mfma_f32_16x16x32_bf16 v[4:7], v[172:175], v[212:215], v[4:7]
	v_mfma_f32_16x16x32_bf16 v[0:3], v[180:183], v[212:215], v[0:3]
	s_setprio 0
	s_barrier
	s_add_i32 s51, 0, 0x18000
	v_add_u32_e32 v155, s51, v146
	v_xor_b32_e32 v253, 64, v155
	s_add_i32 s52, 0, 0x1c000
	ds_read_b128 v[140:143], v155
	ds_read_b128 v[156:159], v253
	ds_read_b128 v[160:163], v155 offset:2048
	ds_read_b128 v[164:167], v253 offset:2048
	v_add_u32_e32 v155, s52, v146
	v_xor_b32_e32 v253, 64, v155
	ds_read_b128 v[168:171], v155
	ds_read_b128 v[172:175], v253
	ds_read_b128 v[176:179], v155 offset:2048
	ds_read_b128 v[180:183], v253 offset:2048
	v_lshl_add_u64 v[242:243], s[20:21], 0, v[128:129]
	s_mov_b32 m0, s26
	v_lshl_add_u64 v[244:245], s[20:21], 0, v[130:131]
	global_load_lds_dwordx4 v[242:243], off
	s_mov_b32 m0, s27
	s_nop 0
	global_load_lds_dwordx4 v[244:245], off
	s_add_u32 s20, s20, 0x404000
	s_addc_u32 s21, s21, 0
	s_mov_b32 m0, s30
	v_lshl_add_u64 v[222:223], s[20:21], 0, v[128:129]
	ds_read_b128 v[184:187], v151 offset:32768
	ds_read_b128 v[188:191], v250 offset:32768
	ds_read_b128 v[192:195], v151 offset:34816
	ds_read_b128 v[196:199], v250 offset:34816
	ds_read_b128 v[200:203], v151 offset:36864
	ds_read_b128 v[204:207], v250 offset:36864
	ds_read_b128 v[208:211], v151 offset:38912
	ds_read_b128 v[212:215], v250 offset:38912
	global_load_lds_dwordx4 v[222:223], off
	v_lshl_add_u64 v[222:223], s[20:21], 0, v[130:131]
	s_mov_b32 m0, s31
	s_nop 0
	global_load_lds_dwordx4 v[222:223], off
	s_waitcnt vmcnt(8)
	s_waitcnt lgkmcnt(0)
	s_barrier
; #define PG8_STAGE(bufoff, gbase, voff) do { _Pragma("unroll") for (int _i = 0; _i < 2; ++_i) \
;         __builtin_amdgcn_global_load_lds((const unsigned*)((const char*)(gbase) + (voff)[_i]), (LAS unsigned*)(lds + (bufoff) + ldsw + _i * 8192), 16, 0, 0); } while (0)
; #define PG8_LDA(dst, b, h) do { _Pragma("unroll") for (int m = 0; m < 4; ++m) _Pragma("unroll") for (int k = 0; k < 2; ++k) dst[m][k] = *(const LAS bf16x8*)(lds + PG8_SA(b, h) + aoff + m * 2048 + k * 1024); } while (0)
; #define PG8_MMA(ai, bj, At, Bt) do { __builtin_amdgcn_s_setprio(3); _Pragma("unroll") for (int m = 0; m < 4; ++m) _Pragma("unroll") for (int n = 0; n < 2; ++n) _Pragma("unroll") for (int k = 0; k < 2; ++k) \
;         acc[ai][bj][m][n] = __builtin_amdgcn_mfma_f32_16x16x32_bf16(Bt[n][k], At[m][k], acc[ai][bj][m][n], 0, 0, 0); __builtin_amdgcn_s_setprio(0); } while (0)
; #define PG8_WAIT_V(n) asm volatile("s_waitcnt vmcnt(" #n ")" ::: "memory")
; #define PG8_WAIT_L(n) asm volatile("s_waitcnt lgkmcnt(" #n ")" ::: "memory")
; #define PG8_BAR __builtin_amdgcn_s_barrier()
; #define PG8_SCHED __builtin_amdgcn_sched_barrier(0)
; template <class Epi, class Sched, bool ALIGN_EPI = false, bool SP2 = false>
; __device__ __forceinline__ void gemm_phase(LAS unsigned char* lds, const Gemm g, const Sched& S, const Epi& E) {
;     ...
;             PG8_WAIT_V(8); PG8_WAIT_L(0); PG8_BAR; PG8_MMA(0, 0, At, B0); PG8_MMA(0, 1, At, B1); PG8_BAR; PG8_SCHED;
;             PG8_LDA(At, 1, 1); PG8_STAGE(PG8_SB(1, 0), b3, voffB); PG8_STAGE(PG8_SB(1, 1), b3 + hsB, voffB); PG8_STAGE(PG8_SA(1, 0), a3, voffA);
;             PG8_WAIT_V(8); PG8_WAIT_L(0); PG8_BAR; PG8_MMA(1, 0, At, B0); PG8_MMA(1, 1, At, B1); PG8_BAR; PG8_SCHED;
	s_setprio 3
	s_waitcnt lgkmcnt(0)
	v_mfma_f32_16x16x32_bf16 v[124:127], v[140:143], v[184:187], v[124:127]
	v_mfma_f32_16x16x32_bf16 v[120:123], v[160:163], v[184:187], v[120:123]
	v_mfma_f32_16x16x32_bf16 v[108:111], v[140:143], v[192:195], v[108:111]
	v_mfma_f32_16x16x32_bf16 v[104:107], v[160:163], v[192:195], v[104:107]
	v_mfma_f32_16x16x32_bf16 v[92:95], v[140:143], v[200:203], v[92:95]
	v_mfma_f32_16x16x32_bf16 v[88:91], v[160:163], v[200:203], v[88:91]
	v_mfma_f32_16x16x32_bf16 v[76:79], v[140:143], v[208:211], v[76:79]
	v_mfma_f32_16x16x32_bf16 v[72:75], v[160:163], v[208:211], v[72:75]
	v_mfma_f32_16x16x32_bf16 v[124:127], v[156:159], v[188:191], v[124:127]
	v_mfma_f32_16x16x32_bf16 v[120:123], v[164:167], v[188:191], v[120:123]
	v_mfma_f32_16x16x32_bf16 v[108:111], v[156:159], v[196:199], v[108:111]
	v_mfma_f32_16x16x32_bf16 v[104:107], v[164:167], v[196:199], v[104:107]
	v_mfma_f32_16x16x32_bf16 v[92:95], v[156:159], v[204:207], v[92:95]
	v_mfma_f32_16x16x32_bf16 v[88:91], v[164:167], v[204:207], v[88:91]
	v_mfma_f32_16x16x32_bf16 v[76:79], v[156:159], v[212:215], v[76:79]
	v_mfma_f32_16x16x32_bf16 v[72:75], v[164:167], v[212:215], v[72:75]
	s_setprio 0
	s_setprio 3
	v_mfma_f32_16x16x32_bf16 v[116:119], v[168:171], v[184:187], v[116:119]
	v_mfma_f32_16x16x32_bf16 v[112:115], v[176:179], v[184:187], v[112:115]
	v_mfma_f32_16x16x32_bf16 v[100:103], v[168:171], v[192:195], v[100:103]
	v_mfma_f32_16x16x32_bf16 v[96:99], v[176:179], v[192:195], v[96:99]
	v_mfma_f32_16x16x32_bf16 v[84:87], v[168:171], v[200:203], v[84:87]
	v_mfma_f32_16x16x32_bf16 v[80:83], v[176:179], v[200:203], v[80:83]
	v_mfma_f32_16x16x32_bf16 v[68:71], v[168:171], v[208:211], v[68:71]
	v_mfma_f32_16x16x32_bf16 v[64:67], v[176:179], v[208:211], v[64:67]
	v_mfma_f32_16x16x32_bf16 v[116:119], v[172:175], v[188:191], v[116:119]
	v_mfma_f32_16x16x32_bf16 v[112:115], v[180:183], v[188:191], v[112:115]
	v_mfma_f32_16x16x32_bf16 v[100:103], v[172:175], v[196:199], v[100:103]
	v_mfma_f32_16x16x32_bf16 v[96:99], v[180:183], v[196:199], v[96:99]
	v_mfma_f32_16x16x32_bf16 v[84:87], v[172:175], v[204:207], v[84:87]
	v_mfma_f32_16x16x32_bf16 v[80:83], v[180:183], v[204:207], v[80:83]
	v_mfma_f32_16x16x32_bf16 v[68:71], v[172:175], v[212:215], v[68:71]
	v_mfma_f32_16x16x32_bf16 v[64:67], v[180:183], v[212:215], v[64:67]
	s_setprio 0
	s_barrier
	s_add_i32 s20, s51, s25
	v_lshl_add_u64 v[144:145], v[144:145], 0, s[8:9]
	s_mov_b32 m0, s20
	ds_read_b128 v[184:187], v151 offset:49152
	ds_read_b128 v[188:191], v250 offset:49152
	ds_read_b128 v[192:195], v151 offset:51200
	ds_read_b128 v[196:199], v250 offset:51200
	ds_read_b128 v[200:203], v151 offset:53248
	ds_read_b128 v[204:207], v250 offset:53248
	ds_read_b128 v[208:211], v151 offset:55296
	ds_read_b128 v[212:215], v250 offset:55296
	global_load_lds_dwordx4 v[144:145], off
	s_add_i32 m0, s20, 0x2000
	s_add_u32 s16, s16, 0x404080
	v_lshl_add_u64 v[144:145], v[216:217], 0, s[8:9]
	s_addc_u32 s17, s17, 0
	s_add_i32 s20, s52, s25
	global_load_lds_dwordx4 v[144:145], off
	v_lshl_add_u64 v[144:145], s[16:17], 0, v[128:129]
	s_mov_b32 m0, s20
	s_nop 0
	global_load_lds_dwordx4 v[144:145], off
	v_lshl_add_u64 v[144:145], s[16:17], 0, v[130:131]
	s_add_i32 m0, s20, 0x2000
	s_nop 0
	global_load_lds_dwordx4 v[144:145], off
	s_waitcnt vmcnt(6)
	s_waitcnt lgkmcnt(0)
	s_barrier
	s_setprio 3
	s_waitcnt lgkmcnt(0)
	v_mfma_f32_16x16x32_bf16 v[60:63], v[140:143], v[184:187], v[60:63]
	v_mfma_f32_16x16x32_bf16 v[56:59], v[160:163], v[184:187], v[56:59]
	v_mfma_f32_16x16x32_bf16 v[44:47], v[140:143], v[192:195], v[44:47]
	v_mfma_f32_16x16x32_bf16 v[40:43], v[160:163], v[192:195], v[40:43]
	v_mfma_f32_16x16x32_bf16 v[28:31], v[140:143], v[200:203], v[28:31]
	v_mfma_f32_16x16x32_bf16 v[24:27], v[160:163], v[200:203], v[24:27]
	v_mfma_f32_16x16x32_bf16 v[12:15], v[140:143], v[208:211], v[12:15]
	v_mfma_f32_16x16x32_bf16 v[8:11], v[160:163], v[208:211], v[8:11]
	v_mfma_f32_16x16x32_bf16 v[60:63], v[156:159], v[188:191], v[60:63]
	v_mfma_f32_16x16x32_bf16 v[56:59], v[164:167], v[188:191], v[56:59]
	v_mfma_f32_16x16x32_bf16 v[44:47], v[156:159], v[196:199], v[44:47]
	v_mfma_f32_16x16x32_bf16 v[40:43], v[164:167], v[196:199], v[40:43]
	v_mfma_f32_16x16x32_bf16 v[28:31], v[156:159], v[204:207], v[28:31]
	v_mfma_f32_16x16x32_bf16 v[24:27], v[164:167], v[204:207], v[24:27]
	v_mfma_f32_16x16x32_bf16 v[12:15], v[156:159], v[212:215], v[12:15]
	v_mfma_f32_16x16x32_bf16 v[8:11], v[164:167], v[212:215], v[8:11]
	s_setprio 0
	s_setprio 3
	v_mfma_f32_16x16x32_bf16 v[52:55], v[168:171], v[184:187], v[52:55]
	v_mfma_f32_16x16x32_bf16 v[48:51], v[176:179], v[184:187], v[48:51]
	v_mfma_f32_16x16x32_bf16 v[36:39], v[168:171], v[192:195], v[36:39]
	v_mfma_f32_16x16x32_bf16 v[32:35], v[176:179], v[192:195], v[32:35]
	v_mfma_f32_16x16x32_bf16 v[20:23], v[168:171], v[200:203], v[20:23]
	v_mfma_f32_16x16x32_bf16 v[16:19], v[176:179], v[200:203], v[16:19]
	v_mfma_f32_16x16x32_bf16 v[4:7], v[168:171], v[208:211], v[4:7]
	v_mfma_f32_16x16x32_bf16 v[0:3], v[176:179], v[208:211], v[0:3]
	v_mfma_f32_16x16x32_bf16 v[52:55], v[172:175], v[188:191], v[52:55]
	v_mfma_f32_16x16x32_bf16 v[48:51], v[180:183], v[188:191], v[48:51]
	v_mfma_f32_16x16x32_bf16 v[36:39], v[172:175], v[196:199], v[36:39]
	v_mfma_f32_16x16x32_bf16 v[32:35], v[180:183], v[196:199], v[32:35]
	v_mfma_f32_16x16x32_bf16 v[20:23], v[172:175], v[204:207], v[20:23]
	v_mfma_f32_16x16x32_bf16 v[16:19], v[180:183], v[204:207], v[16:19]
	v_mfma_f32_16x16x32_bf16 v[4:7], v[172:175], v[212:215], v[4:7]
	v_mfma_f32_16x16x32_bf16 v[0:3], v[180:183], v[212:215], v[0:3]
	s_setprio 0
	s_barrier
	s_add_i32 s50, s50, 2
	s_add_u32 s14, s14, 0x100
	s_addc_u32 s15, s15, 0
	s_add_u32 s48, s48, 0x100
	s_addc_u32 s49, s49, 0
	s_cmpk_gt_u32 s50, 0xfd
	s_cbranch_scc0 .LBB0_350
	s_and_b64 vcc, exec, s[10:11]
	s_cbranch_vccz .LBB0_353
	s_barrier
